# gdn_prep conv+silu+l2norm section rewritten by hand: conv weights staged in LDS, 6-deep rotating prefetch of PROJ taps issued before the gate section, branch-free tap masking, rcp+mul silu
# speedup vs baseline: 1.1642x; 1.0448x over previous
.LBB0_212:
	s_and_b64 vcc, exec, s[0:1]
	s_cbranch_vccz .LBB0_446
	s_add_i32 s64, s36, 0xffffff00
	s_and_b32 s15, s36, 31
	s_lshr_b32 s14, s64, 7
	s_bfe_u32 s16, s36, 0x20005
	s_lshl_b32 s18, s15, 6
	s_lshl_b32 s19, s14, 11
	s_barrier
	s_bfe_u32 s68, s64, 0x20005
	s_lshr_b32 s69, s64, 7
	s_and_b32 s70, s64, 31
	v_readlane_b32 s72, v251, 28
	v_readlane_b32 s73, v251, 29
	s_lshl_b32 s71, s68, 9
	s_mul_i32 s74, s69, 0xa00000
	s_lshl_b32 s75, s68, 8
	s_add_u32 s74, s74, s75
	s_add_u32 s74, s74, 0x400
	s_add_u32 s76, s28, s74
	s_addc_u32 s77, s29, 0
	s_add_u32 s72, s72, s71
	s_addc_u32 s73, s73, 0
	s_lshl_b32 s78, s70, 6
	s_sub_u32 s78, s78, 3
	v_lshrrev_b32_e32 v64, 2, v162
	v_and_b32_e32 v65, 3, v162
	v_add_u32_e32 v66, s78, v64
	v_mov_b32_e32 v67, v66
	v_max_i32_e32 v67, 0, v67
	v_mul_u32_u24_e32 v67, 0x1400, v67
	v_lshl_add_u32 v248, v65, 6, v67
	v_add_u32_e32 v67, 1, v66
	v_max_i32_e32 v67, 0, v67
	v_mul_u32_u24_e32 v67, 0x1400, v67
	v_lshl_add_u32 v249, v65, 6, v67
	v_add_u32_e32 v67, 2, v66
	v_max_i32_e32 v67, 0, v67
	v_mul_u32_u24_e32 v67, 0x1400, v67
	v_lshl_add_u32 v253, v65, 6, v67
	v_add_u32_e32 v67, 3, v66
	v_max_i32_e32 v67, 0, v67
	v_mul_u32_u24_e32 v67, 0x1400, v67
	v_lshl_add_u32 v254, v65, 6, v67
	v_lshrrev_b32_e32 v66, 5, v162
	v_and_b32_e32 v67, 31, v162
	v_lshlrev_b32_e32 v68, 11, v66
	v_lshl_add_u32 v68, v67, 4, v68
	v_mul_u32_u24_e32 v69, 0x240, v66
	v_lshrrev_b32_e32 v70, 3, v67
	v_mul_u32_u24_e32 v70, 0x90, v70
	v_and_b32_e32 v71, 7, v67
	v_lshl_add_u32 v70, v71, 4, v70
	v_add_u32_e32 v69, v69, v70
	v_add_u32_e32 v22, 0xc400, v69
	v_cmp_gt_u32_e32 vcc, 0x80, v162
	v_mov_b32_e32 v71, 0x4000
	v_mov_b32_e32 v70, 0x1200
	s_nop 1
	v_cndmask_b32_e32 v71, 0, v71, vcc
	v_cndmask_b32_e32 v70, 0, v70, vcc
	v_add_u32_e32 v69, v68, v71
	v_add_u32_e32 v23, v22, v70
	global_load_dwordx4 v[56:59], v68, s[72:73]
	global_load_dwordx4 v[60:63], v69, s[72:73]
	global_load_dwordx4 v[28:31], v248, s[76:77] offset:0
	global_load_dwordx4 v[32:35], v249, s[76:77] offset:0
	global_load_dwordx4 v[36:39], v253, s[76:77] offset:0
	global_load_dwordx4 v[40:43], v254, s[76:77] offset:0
	global_load_dwordx4 v[44:47], v248, s[76:77] offset:16
	global_load_dwordx4 v[52:55], v249, s[76:77] offset:16
	s_and_saveexec_b64 s[0:1], s[10:11]
	s_cbranch_execz .LBB0_215
	s_or_b32 s17, s18, s19
	v_or_b32_e32 v0, s17, v162
	v_readlane_b32 s68, v251, 8
	v_lshlrev_b32_e32 v0, 3, v0
	v_readlane_b32 s69, v251, 9
	v_readlane_b32 s70, v251, 10
	v_readlane_b32 s71, v251, 11
	v_readlane_b32 s72, v251, 12
	v_readlane_b32 s73, v251, 13
	v_readlane_b32 s74, v251, 14
	v_readlane_b32 s75, v251, 15
	v_readlane_b32 s76, v251, 16
	v_readlane_b32 s77, v251, 17
	v_readlane_b32 s78, v251, 18
	v_readlane_b32 s79, v251, 19
	v_readlane_b32 s80, v251, 20
	v_readlane_b32 s81, v251, 21
	v_readlane_b32 s82, v251, 22
	v_readlane_b32 s83, v251, 23
	v_lshl_add_u64 v[2:3], v[0:1], 2, s[74:75]
	v_readlane_b32 s68, v251, 24
	s_lshl_b32 s8, s16, 2
	v_readlane_b32 s69, v251, 25
	v_readlane_b32 s70, v251, 26
	v_readlane_b32 s71, v251, 27
	v_readlane_b32 s72, v251, 28
	v_readlane_b32 s73, v251, 29
	v_readlane_b32 s74, v251, 30
	v_readlane_b32 s75, v251, 31
	v_lshl_add_u64 v[2:3], v[2:3], 0, s[8:9]
	v_readlane_b32 s76, v251, 32
	v_readlane_b32 s77, v251, 33
	v_readlane_b32 s78, v251, 34
	v_readlane_b32 s79, v251, 35
	s_mov_b64 s[68:69], s[72:73]
	global_load_dword v0, v[2:3], off
	s_mov_b64 s[70:71], s[74:75]
	global_load_dword v2, v[2:3], off offset:16
	v_mov_b32_e32 v3, s8
	s_mov_b64 s[72:73], s[76:77]
	global_load_dword v8, v3, s[72:73]
	s_mov_b32 s8, 0xbfb8aa3b
	s_mov_b32 s17, 0xb2a5705f
	global_load_dword v3, v3, s[70:71]
	v_readlane_b32 s12, v252, 34
	v_readlane_b32 s13, v252, 35
	v_readlane_b32 s80, v251, 36
	v_readlane_b32 s81, v251, 37
	v_readlane_b32 s82, v251, 38
	v_readlane_b32 s83, v251, 39
	s_mov_b64 s[74:75], s[78:79]
	s_waitcnt vmcnt(3)
	v_mul_f32_e32 v0, 0xbfb8aa3b, v0
	v_exp_f32_e32 v0, v0
	s_waitcnt vmcnt(1)
	v_add_f32_e32 v2, v2, v8
	v_mul_f32_e64 v8, |v2|, s8
	v_fma_f32 v9, |v2|, s8, -v8
	v_rndne_f32_e32 v11, v8
	v_fma_f32 v9, |v2|, s17, v9
	v_sub_f32_e32 v8, v8, v11
	v_add_f32_e32 v8, v8, v9
	v_exp_f32_e32 v8, v8
	v_cvt_i32_f32_e32 v9, v11
	s_mov_b32 s17, 0x42ce8ed0
	v_cmp_ngt_f32_e64 vcc, |v2|, s17
	s_mov_b32 s17, 0xc2b17218
	v_ldexp_f32 v8, v8, v9
	v_cndmask_b32_e32 v8, 0, v8, vcc
	v_cmp_nlt_f32_e64 vcc, |v2|, s17
	v_max_f32_e32 v10, 0, v2
	s_mov_b32 s17, 0x3f2aaaab
	v_cndmask_b32_e32 v2, v207, v8, vcc
	v_add_f32_e32 v11, 1.0, v2
	v_add_f32_e32 v8, -1.0, v11
	v_sub_f32_e32 v9, v8, v11
	v_add_f32_e32 v9, 1.0, v9
	v_sub_f32_e32 v8, v2, v8
	v_add_f32_e32 v12, v8, v9
	v_frexp_mant_f32_e32 v8, v11
	v_cmp_gt_f32_e32 vcc, s17, v8
	v_cvt_f64_f32_e32 v[8:9], v11
	v_frexp_exp_i32_f64_e32 v8, v[8:9]
	v_subbrev_co_u32_e32 v8, vcc, 0, v8, vcc
	v_sub_u32_e32 v9, 0, v8
	v_ldexp_f32 v11, v11, v9
	v_ldexp_f32 v9, v12, v9
	v_add_f32_e32 v12, -1.0, v11
	v_add_f32_e32 v13, 1.0, v12
	v_sub_f32_e32 v13, v11, v13
	v_add_f32_e32 v13, v9, v13
	v_add_f32_e32 v14, v12, v13
	v_sub_f32_e32 v12, v12, v14
	v_add_f32_e32 v12, v13, v12
	v_add_f32_e32 v13, 1.0, v11
	v_add_f32_e32 v15, -1.0, v13
	v_sub_f32_e32 v11, v11, v15
	v_add_f32_e32 v9, v9, v11
	v_add_f32_e32 v11, v13, v9
	v_sub_f32_e32 v13, v13, v11
	v_add_f32_e32 v9, v9, v13
	v_rcp_f32_e32 v13, v11
	v_cvt_f32_i32_e32 v8, v8
	s_mov_b32 s17, 0x3f317218
	v_cmp_neq_f32_e32 vcc, s37, v2
	v_mul_f32_e32 v15, v14, v13
	v_mul_f32_e32 v16, v11, v15
	v_fma_f32 v17, v15, v11, -v16
	v_fmac_f32_e32 v17, v15, v9
	v_add_f32_e32 v18, v16, v17
	v_sub_f32_e32 v19, v14, v18
	v_sub_f32_e32 v14, v14, v19
	v_sub_f32_e32 v16, v18, v16
	v_sub_f32_e32 v14, v14, v18
	v_add_f32_e32 v12, v12, v14
	v_sub_f32_e32 v14, v16, v17
	v_add_f32_e32 v12, v14, v12
	v_add_f32_e32 v14, v19, v12
	v_mul_f32_e32 v16, v13, v14
	v_mul_f32_e32 v17, v11, v16
	v_fma_f32 v11, v16, v11, -v17
	v_fmac_f32_e32 v11, v16, v9
	v_sub_f32_e32 v9, v19, v14
	v_add_f32_e32 v9, v12, v9
	v_add_f32_e32 v12, v17, v11
	v_sub_f32_e32 v18, v14, v12
	v_sub_f32_e32 v14, v14, v18
	v_sub_f32_e32 v17, v12, v17
	v_sub_f32_e32 v12, v14, v12
	v_add_f32_e32 v9, v9, v12
	v_sub_f32_e32 v11, v17, v11
	v_add_f32_e32 v9, v11, v9
	v_add_f32_e32 v11, v15, v16
	v_add_f32_e32 v9, v18, v9
	v_sub_f32_e32 v12, v11, v15
	v_mul_f32_e32 v9, v13, v9
	v_sub_f32_e32 v12, v16, v12
	v_add_f32_e32 v9, v12, v9
	v_mul_f32_e32 v15, 0x3f317218, v8
	v_add_f32_e32 v12, v11, v9
	v_fma_f32 v16, v8, s17, -v15
	v_mul_f32_e32 v13, v12, v12
	v_fmac_f32_e32 v16, 0xb102e308, v8
	v_sub_f32_e32 v8, v12, v11
	v_fmamk_f32 v14, v13, 0x3e9b6dac, v197
	v_sub_f32_e32 v8, v9, v8
	v_add_f32_e32 v9, v15, v16
	v_fmaak_f32 v14, v13, v14, 0x3f2aaada
	v_sub_f32_e32 v11, v9, v15
	v_ldexp_f32 v15, v12, 1
	v_mul_f32_e32 v12, v12, v13
	v_mul_f32_e32 v12, v12, v14
	v_add_f32_e32 v13, v15, v12
	v_sub_f32_e32 v14, v13, v15
	v_ldexp_f32 v8, v8, 1
	v_sub_f32_e32 v12, v12, v14
	v_add_f32_e32 v8, v8, v12
	v_add_f32_e32 v12, v13, v8
	v_sub_f32_e32 v13, v12, v13
	v_sub_f32_e32 v8, v8, v13
	v_add_f32_e32 v13, v9, v12
	v_sub_f32_e32 v14, v13, v9
	v_sub_f32_e32 v15, v13, v14
	v_sub_f32_e32 v11, v16, v11
	v_sub_f32_e32 v9, v9, v15
	v_sub_f32_e32 v12, v12, v14
	v_add_f32_e32 v9, v12, v9
	v_add_f32_e32 v12, v11, v8
	v_sub_f32_e32 v14, v12, v11
	v_sub_f32_e32 v15, v12, v14
	v_sub_f32_e32 v11, v11, v15
	v_sub_f32_e32 v8, v8, v14
	v_add_f32_e32 v9, v12, v9
	v_add_f32_e32 v8, v8, v11
	v_add_f32_e32 v11, v13, v9
	v_sub_f32_e32 v12, v11, v13
	v_sub_f32_e32 v9, v9, v12
	v_add_f32_e32 v8, v8, v9
	v_add_f32_e32 v8, v11, v8
	s_mov_b32 s17, 0x33800000
	v_cndmask_b32_e32 v8, v207, v8, vcc
	v_cmp_lt_f32_e64 vcc, |v2|, s17
	v_add_f32_e32 v0, 1.0, v0
	s_nop 0
	v_cndmask_b32_e32 v2, v8, v2, vcc
	s_waitcnt vmcnt(0)
	v_mul_f32_e32 v8, 0x3fb8aa3b, v3
	v_add_f32_e32 v2, v10, v2
	v_fma_f32 v9, v3, s86, -v8
	v_rndne_f32_e32 v10, v8
	v_fmac_f32_e32 v9, 0x32a5705f, v3
	v_sub_f32_e32 v8, v8, v10
	v_add_f32_e32 v8, v8, v9
	v_exp_f32_e32 v8, v8
	v_cvt_i32_f32_e32 v9, v10
	v_cmp_ngt_f32_e32 vcc, s87, v3
	v_add_u32_e32 v10, -1, v154
	v_ldexp_f32 v8, v8, v9
	v_cndmask_b32_e32 v8, 0, v8, vcc
	v_cmp_nlt_f32_e32 vcc, s88, v3
	v_and_b32_e32 v3, 64, v154
	s_nop 0
	v_cndmask_b32_e32 v8, v207, v8, vcc
	v_cmp_lt_i32_e32 vcc, v10, v3
	v_mul_f32_e64 v9, v2, -v8
	s_nop 0
	v_cndmask_b32_e32 v10, v10, v154, vcc
	v_lshlrev_b32_e32 v10, 2, v10
	ds_bpermute_b32 v10, v10, v9
	s_waitcnt lgkmcnt(0)
	v_fma_f32 v2, v2, -v8, v10
	v_add_u32_e32 v8, -2, v154
	v_cmp_lt_i32_e32 vcc, v8, v3
	v_cndmask_b32_e64 v2, v2, v9, s[66:67]
	s_nop 0
	v_cndmask_b32_e32 v8, v8, v154, vcc
	v_lshlrev_b32_e32 v8, 2, v8
	ds_bpermute_b32 v8, v8, v2
	s_waitcnt lgkmcnt(0)
	v_add_f32_e32 v8, v2, v8
	v_cndmask_b32_e64 v2, v8, v2, s[12:13]
	v_add_u32_e32 v8, -4, v154
	v_cmp_lt_i32_e32 vcc, v8, v3
	v_readlane_b32 s12, v252, 36
	v_readlane_b32 s13, v252, 37
	v_cndmask_b32_e32 v8, v8, v154, vcc
	v_lshlrev_b32_e32 v8, 2, v8
	ds_bpermute_b32 v8, v8, v2
	s_waitcnt lgkmcnt(0)
	v_add_f32_e32 v8, v2, v8
	v_cndmask_b32_e64 v2, v8, v2, s[12:13]
	v_add_u32_e32 v8, -8, v154
	v_cmp_lt_i32_e32 vcc, v8, v3
	v_readlane_b32 s12, v252, 38
	v_readlane_b32 s13, v252, 39
	v_cndmask_b32_e32 v8, v8, v154, vcc
	v_lshlrev_b32_e32 v8, 2, v8
	ds_bpermute_b32 v8, v8, v2
	s_waitcnt lgkmcnt(0)
	v_add_f32_e32 v8, v2, v8
	v_cndmask_b32_e64 v2, v8, v2, s[12:13]
	v_add_u32_e32 v8, -16, v154
	v_cmp_lt_i32_e32 vcc, v8, v3
	v_readlane_b32 s12, v252, 40
	v_readlane_b32 s13, v252, 41
	v_cndmask_b32_e32 v8, v8, v154, vcc
	v_lshlrev_b32_e32 v8, 2, v8
	ds_bpermute_b32 v8, v8, v2
	s_waitcnt lgkmcnt(0)
	v_add_f32_e32 v8, v2, v8
	v_cndmask_b32_e64 v2, v8, v2, s[12:13]
	v_subrev_u32_e32 v8, 32, v154
	v_cmp_lt_i32_e32 vcc, v8, v3
	s_nop 1
	v_cndmask_b32_e32 v3, v8, v154, vcc
	v_lshlrev_b32_e32 v3, 2, v3
	ds_bpermute_b32 v3, v3, v2
	s_waitcnt lgkmcnt(0)
	v_add_f32_e32 v3, v2, v3
	v_cndmask_b32_e64 v2, v3, v2, s[4:5]
	v_div_scale_f32 v3, s[92:93], v0, v0, 1.0
	v_rcp_f32_e32 v8, v3
	s_nop 0
	v_fma_f32 v9, -v3, v8, 1.0
	v_fmac_f32_e32 v8, v9, v8
	v_div_scale_f32 v9, vcc, 1.0, v0, 1.0
	v_mul_f32_e32 v10, v9, v8
	v_fma_f32 v11, -v3, v10, v9
	v_fmac_f32_e32 v10, v11, v8
	v_fma_f32 v3, -v3, v10, v9
	v_div_fmas_f32 v3, v3, v8, v10
	v_div_fixup_f32 v0, v3, v0, 1.0
	ds_write2st64_b32 v140, v2, v0 offset0:192 offset1:193
	v_mul_f32_e32 v0, 0x3fb8aa3b, v2
	v_fma_f32 v3, v2, s86, -v0
	v_rndne_f32_e32 v8, v0
	v_fmac_f32_e32 v3, 0x32a5705f, v2
	v_sub_f32_e32 v0, v0, v8
	v_add_f32_e32 v0, v0, v3
	v_exp_f32_e32 v0, v0
	v_cvt_i32_f32_e32 v3, v8
	v_cmp_ngt_f32_e32 vcc, s87, v2
	v_ldexp_f32 v0, v0, v3
	s_nop 0
	v_cndmask_b32_e32 v0, 0, v0, vcc
	v_cmp_nlt_f32_e32 vcc, s88, v2
	s_nop 1
	v_cndmask_b32_e32 v0, v207, v0, vcc
	ds_write_b32 v140, v0 offset:49664
.LBB0_215:
	s_or_b64 exec, exec, s[0:1]
	s_waitcnt vmcnt(6)
	ds_write_b128 v22, v[56:59]
	ds_write_b128 v23, v[60:63]
	s_lshl_b32 s16, s16, 7
	s_cmp_lg_u32 s15, 31
	s_waitcnt lgkmcnt(0)
	s_barrier
	s_cbranch_scc1 .LBB0_219
	v_readlane_b32 s68, v251, 56
	s_or_b32 s15, s19, 0x7fd
	s_mul_i32 s14, s14, 3
	s_mov_b64 s[0:1], 0
	v_mov_b32_e32 v0, v162
	v_readlane_b32 s69, v251, 57
	v_readlane_b32 s70, v251, 58
	v_readlane_b32 s71, v251, 59
	v_readlane_b32 s72, v251, 60
	v_readlane_b32 s73, v251, 61
	v_readlane_b32 s74, v251, 62
	v_readlane_b32 s75, v251, 63
	v_readlane_b32 s76, v252, 0
	v_readlane_b32 s77, v252, 1
	v_readlane_b32 s78, v252, 2
	v_readlane_b32 s79, v252, 3
	v_readlane_b32 s80, v252, 4
	v_readlane_b32 s81, v252, 5
	v_readlane_b32 s82, v252, 6
	v_readlane_b32 s83, v252, 7

.LBB0_219:
	s_and_b32 s15, s64, 31
	s_bfe_u32 s14, s64, 0x20005
	s_lshr_b32 s0, s64, 7
	s_mul_i32 s8, s0, 0xa00000
	s_lshl_b32 s1, s14, 8
	s_add_u32 s8, s8, s1
	s_add_u32 s8, s8, 0x400
	s_add_u32 s16, s28, s8
	s_addc_u32 s17, s29, 0
	s_mov_b32 s18, 0xbfb8aa3b
	s_mov_b32 s19, 0
	s_mul_i32 s0, s64, 0x12000
	s_mul_hi_u32 s1, s64, 0x12000
	s_add_u32 s92, s30, s0
	s_addc_u32 s93, s31, s1
	v_lshrrev_b32_e32 v119, 2, v162
	v_and_b32_e32 v121, 3, v162
	v_mul_u32_u24_e32 v255, 0x90, v121
	v_add_u32_e32 v255, 0xc400, v255
	v_lshlrev_b32_e32 v0, 2, v119
	ds_read_b32 v230, v0 offset:49664
	ds_read_b32 v216, v0 offset:49152
	ds_read_b32 v217, v1 offset:49404
	ds_read_b128 v[48:51], v255 offset:0
	ds_read_b128 v[56:59], v255 offset:16
	ds_read_b128 v[60:63], v255 offset:1728
	ds_read_b128 v[220:223], v255 offset:1744
	v_lshlrev_b32_e32 v111, 8, v119
	v_and_b32_e32 v0, 15, v119
	v_lshlrev_b32_e32 v113, 2, v121
	v_xor_b32_e32 v113, v113, v0
	v_lshlrev_b32_e32 v115, 12, v121
	v_lshl_add_u32 v115, v119, 1, v115
	v_add_u32_e32 v115, 0xc000, v115
	v_lshl_add_u32 v117, v121, 6, v111
	v_add_u32_e32 v117, 0x8000, v117
	s_lshl_b32 s0, s15, 6
	s_sub_u32 s0, s0, 3
	v_add_u32_e32 v121, s0, v119
	v_cmp_lt_i32_e64 s[70:71], -1, v121
	v_add_u32_e32 v121, 1, v121
	v_cmp_lt_i32_e64 s[72:73], -1, v121
	v_add_u32_e32 v121, 1, v121
	v_cmp_lt_i32_e64 s[74:75], -1, v121
	s_waitcnt lgkmcnt(4)
	v_sub_f32_e32 v119, v217, v216
	v_mul_f32_e32 v121, 0x3fb8aa3b, v119
	v_fma_f32 v0, v119, s86, -v121
	v_rndne_f32_e32 v216, v121
	v_fmac_f32_e32 v0, 0x32a5705f, v119
	v_sub_f32_e32 v121, v121, v216
	v_add_f32_e32 v121, v121, v0
	v_exp_f32_e32 v121, v121
	v_cvt_i32_f32_e32 v0, v216
	v_cmp_ngt_f32_e32 vcc, s87, v119
	v_ldexp_f32 v121, v121, v0
	s_nop 0
	v_cndmask_b32_e32 v121, 0, v121, vcc
	v_cmp_nlt_f32_e32 vcc, s88, v119
	v_mov_b32_e32 v0, 0x7f800000
	s_nop 1
	v_cndmask_b32_e32 v231, v0, v121, vcc
	v_mov_b32_e32 v218, 0
	s_cmp_lg_u32 s15, 0
	s_cbranch_scc1 .Lpb_sk_0
	s_waitcnt vmcnt(3)
	v_cndmask_b32_e64 v28, 0, v28, s[70:71]
	v_cndmask_b32_e64 v29, 0, v29, s[70:71]
	v_cndmask_b32_e64 v30, 0, v30, s[70:71]
	v_cndmask_b32_e64 v31, 0, v31, s[70:71]
	v_cndmask_b32_e64 v32, 0, v32, s[72:73]
	v_cndmask_b32_e64 v33, 0, v33, s[72:73]
	v_cndmask_b32_e64 v34, 0, v34, s[72:73]
	v_cndmask_b32_e64 v35, 0, v35, s[72:73]
	v_cndmask_b32_e64 v36, 0, v36, s[74:75]
	v_cndmask_b32_e64 v37, 0, v37, s[74:75]
	v_cndmask_b32_e64 v38, 0, v38, s[74:75]
	v_cndmask_b32_e64 v39, 0, v39, s[74:75]
.Lpb_sk_0:
	s_waitcnt vmcnt(5)
	v_lshlrev_b32_e32 v224, 16, v28
	v_and_b32_e32 v225, 0xffff0000, v28
	v_lshlrev_b32_e32 v226, 16, v29
	v_and_b32_e32 v227, 0xffff0000, v29
	s_waitcnt lgkmcnt(3)
	v_pk_fma_f32 v[126:127], v[48:49], v[224:225], 0 op_sel_hi:[1,1,0]
	v_pk_fma_f32 v[128:129], v[50:51], v[226:227], 0 op_sel_hi:[1,1,0]
	ds_read_b128 v[48:51], v255 offset:3456
	v_lshlrev_b32_e32 v224, 16, v30
	v_and_b32_e32 v225, 0xffff0000, v30
	v_lshlrev_b32_e32 v226, 16, v31
	v_and_b32_e32 v227, 0xffff0000, v31
	s_waitcnt lgkmcnt(3)
	v_pk_fma_f32 v[130:131], v[56:57], v[224:225], 0 op_sel_hi:[1,1,0]
	v_pk_fma_f32 v[132:133], v[58:59], v[226:227], 0 op_sel_hi:[1,1,0]
	ds_read_b128 v[56:59], v255 offset:3472
	global_load_dwordx4 v[28:31], v253, s[16:17] offset:16
	s_waitcnt vmcnt(5)
	v_lshlrev_b32_e32 v224, 16, v32
	v_and_b32_e32 v225, 0xffff0000, v32
	v_lshlrev_b32_e32 v226, 16, v33
	v_and_b32_e32 v227, 0xffff0000, v33
	s_waitcnt lgkmcnt(3)
	v_pk_fma_f32 v[126:127], v[60:61], v[224:225], v[126:127]
	v_pk_fma_f32 v[128:129], v[62:63], v[226:227], v[128:129]
	ds_read_b128 v[60:63], v255 offset:5184
	v_lshlrev_b32_e32 v224, 16, v34
	v_and_b32_e32 v225, 0xffff0000, v34
	v_lshlrev_b32_e32 v226, 16, v35
	v_and_b32_e32 v227, 0xffff0000, v35
	s_waitcnt lgkmcnt(3)
	v_pk_fma_f32 v[130:131], v[220:221], v[224:225], v[130:131]
	v_pk_fma_f32 v[132:133], v[222:223], v[226:227], v[132:133]
	ds_read_b128 v[220:223], v255 offset:5200
	global_load_dwordx4 v[32:35], v254, s[16:17] offset:16
	s_waitcnt vmcnt(5)
	v_lshlrev_b32_e32 v224, 16, v36
	v_and_b32_e32 v225, 0xffff0000, v36
	v_lshlrev_b32_e32 v226, 16, v37
	v_and_b32_e32 v227, 0xffff0000, v37
	s_waitcnt lgkmcnt(3)
	v_pk_fma_f32 v[126:127], v[48:49], v[224:225], v[126:127]
	v_pk_fma_f32 v[128:129], v[50:51], v[226:227], v[128:129]
	ds_read_b128 v[48:51], v255 offset:32
	v_lshlrev_b32_e32 v224, 16, v38
	v_and_b32_e32 v225, 0xffff0000, v38
	v_lshlrev_b32_e32 v226, 16, v39
	v_and_b32_e32 v227, 0xffff0000, v39
	s_waitcnt lgkmcnt(3)
	v_pk_fma_f32 v[130:131], v[56:57], v[224:225], v[130:131]
	v_pk_fma_f32 v[132:133], v[58:59], v[226:227], v[132:133]
	ds_read_b128 v[56:59], v255 offset:48
	global_load_dwordx4 v[36:39], v248, s[16:17] offset:32
	s_waitcnt vmcnt(5)
	v_lshlrev_b32_e32 v224, 16, v40
	v_and_b32_e32 v225, 0xffff0000, v40
	v_lshlrev_b32_e32 v226, 16, v41
	v_and_b32_e32 v227, 0xffff0000, v41
	s_waitcnt lgkmcnt(3)
	v_pk_fma_f32 v[126:127], v[60:61], v[224:225], v[126:127]
	v_pk_fma_f32 v[128:129], v[62:63], v[226:227], v[128:129]
	ds_read_b128 v[60:63], v255 offset:1760
	v_lshlrev_b32_e32 v224, 16, v42
	v_and_b32_e32 v225, 0xffff0000, v42
	v_lshlrev_b32_e32 v226, 16, v43
	v_and_b32_e32 v227, 0xffff0000, v43
	s_waitcnt lgkmcnt(3)
	v_pk_fma_f32 v[130:131], v[220:221], v[224:225], v[130:131]
	v_pk_fma_f32 v[132:133], v[222:223], v[226:227], v[132:133]
	ds_read_b128 v[220:223], v255 offset:1776
	global_load_dwordx4 v[40:43], v249, s[16:17] offset:32
	v_pk_mul_f32 v[224:225], v[126:127], s[18:19] op_sel_hi:[1,0]
	v_pk_mul_f32 v[226:227], v[128:129], s[18:19] op_sel_hi:[1,0]
	v_pk_mul_f32 v[2:3], v[130:131], s[18:19] op_sel_hi:[1,0]
	v_pk_mul_f32 v[134:135], v[132:133], s[18:19] op_sel_hi:[1,0]
	v_exp_f32_e32 v224, v224
	v_exp_f32_e32 v225, v225
	v_exp_f32_e32 v226, v226
	v_exp_f32_e32 v227, v227
	v_exp_f32_e32 v2, v2
	v_exp_f32_e32 v3, v3
	v_exp_f32_e32 v134, v134
	v_exp_f32_e32 v135, v135
	v_pk_add_f32 v[224:225], v[224:225], 1.0 op_sel_hi:[1,0]
	v_pk_add_f32 v[226:227], v[226:227], 1.0 op_sel_hi:[1,0]
	v_pk_add_f32 v[2:3], v[2:3], 1.0 op_sel_hi:[1,0]
	v_pk_add_f32 v[134:135], v[134:135], 1.0 op_sel_hi:[1,0]
	v_rcp_f32_e32 v224, v224
	v_rcp_f32_e32 v225, v225
	v_rcp_f32_e32 v226, v226
	v_rcp_f32_e32 v227, v227
	v_rcp_f32_e32 v2, v2
	v_rcp_f32_e32 v3, v3
	v_rcp_f32_e32 v134, v134
	v_rcp_f32_e32 v135, v135
	v_pk_mul_f32 v[8:9], v[126:127], v[224:225]
	v_pk_mul_f32 v[10:11], v[128:129], v[226:227]
	v_pk_mul_f32 v[12:13], v[130:131], v[2:3]
	v_pk_mul_f32 v[14:15], v[132:133], v[134:135]
	v_pk_mul_f32 v[216:217], v[8:9], v[8:9]
	v_add_f32_e32 v218, v218, v216
	v_add_f32_e32 v218, v217, v218
	v_pk_mul_f32 v[216:217], v[10:11], v[10:11]
	v_add_f32_e32 v218, v218, v216
	v_add_f32_e32 v218, v217, v218
	v_pk_mul_f32 v[216:217], v[12:13], v[12:13]
	v_add_f32_e32 v218, v218, v216
	v_add_f32_e32 v218, v217, v218
	v_pk_mul_f32 v[216:217], v[14:15], v[14:15]
	v_add_f32_e32 v218, v218, v216
	v_add_f32_e32 v218, v217, v218
	s_cmp_lg_u32 s15, 0
	s_cbranch_scc1 .Lpb_sk_1
	s_waitcnt vmcnt(3)
	v_cndmask_b32_e64 v44, 0, v44, s[70:71]
	v_cndmask_b32_e64 v45, 0, v45, s[70:71]
	v_cndmask_b32_e64 v46, 0, v46, s[70:71]
	v_cndmask_b32_e64 v47, 0, v47, s[70:71]
	v_cndmask_b32_e64 v52, 0, v52, s[72:73]
	v_cndmask_b32_e64 v53, 0, v53, s[72:73]
	v_cndmask_b32_e64 v54, 0, v54, s[72:73]
	v_cndmask_b32_e64 v55, 0, v55, s[72:73]
	v_cndmask_b32_e64 v28, 0, v28, s[74:75]
	v_cndmask_b32_e64 v29, 0, v29, s[74:75]
	v_cndmask_b32_e64 v30, 0, v30, s[74:75]
	v_cndmask_b32_e64 v31, 0, v31, s[74:75]
.Lpb_sk_1:
	s_waitcnt vmcnt(5)
	v_lshlrev_b32_e32 v224, 16, v44
	v_and_b32_e32 v225, 0xffff0000, v44
	v_lshlrev_b32_e32 v226, 16, v45
	v_and_b32_e32 v227, 0xffff0000, v45
	s_waitcnt lgkmcnt(3)
	v_pk_fma_f32 v[126:127], v[48:49], v[224:225], 0 op_sel_hi:[1,1,0]
	v_pk_fma_f32 v[128:129], v[50:51], v[226:227], 0 op_sel_hi:[1,1,0]
	ds_read_b128 v[48:51], v255 offset:3488
	v_lshlrev_b32_e32 v224, 16, v46
	v_and_b32_e32 v225, 0xffff0000, v46
	v_lshlrev_b32_e32 v226, 16, v47
	v_and_b32_e32 v227, 0xffff0000, v47
	s_waitcnt lgkmcnt(3)
	v_pk_fma_f32 v[130:131], v[56:57], v[224:225], 0 op_sel_hi:[1,1,0]
	v_pk_fma_f32 v[132:133], v[58:59], v[226:227], 0 op_sel_hi:[1,1,0]
	ds_read_b128 v[56:59], v255 offset:3504
	global_load_dwordx4 v[44:47], v253, s[16:17] offset:32
	s_waitcnt vmcnt(5)
	v_lshlrev_b32_e32 v224, 16, v52
	v_and_b32_e32 v225, 0xffff0000, v52
	v_lshlrev_b32_e32 v226, 16, v53
	v_and_b32_e32 v227, 0xffff0000, v53
	s_waitcnt lgkmcnt(3)
	v_pk_fma_f32 v[126:127], v[60:61], v[224:225], v[126:127]
	v_pk_fma_f32 v[128:129], v[62:63], v[226:227], v[128:129]
	ds_read_b128 v[60:63], v255 offset:5216
	v_lshlrev_b32_e32 v224, 16, v54
	v_and_b32_e32 v225, 0xffff0000, v54
	v_lshlrev_b32_e32 v226, 16, v55
	v_and_b32_e32 v227, 0xffff0000, v55
	s_waitcnt lgkmcnt(3)
	v_pk_fma_f32 v[130:131], v[220:221], v[224:225], v[130:131]
	v_pk_fma_f32 v[132:133], v[222:223], v[226:227], v[132:133]
	ds_read_b128 v[220:223], v255 offset:5232
	global_load_dwordx4 v[52:55], v254, s[16:17] offset:32
	s_waitcnt vmcnt(5)
	v_lshlrev_b32_e32 v224, 16, v28
	v_and_b32_e32 v225, 0xffff0000, v28
	v_lshlrev_b32_e32 v226, 16, v29
	v_and_b32_e32 v227, 0xffff0000, v29
	s_waitcnt lgkmcnt(3)
	v_pk_fma_f32 v[126:127], v[48:49], v[224:225], v[126:127]
	v_pk_fma_f32 v[128:129], v[50:51], v[226:227], v[128:129]
	ds_read_b128 v[48:51], v255 offset:64
	v_lshlrev_b32_e32 v224, 16, v30
	v_and_b32_e32 v225, 0xffff0000, v30
	v_lshlrev_b32_e32 v226, 16, v31
	v_and_b32_e32 v227, 0xffff0000, v31
	s_waitcnt lgkmcnt(3)
	v_pk_fma_f32 v[130:131], v[56:57], v[224:225], v[130:131]
	v_pk_fma_f32 v[132:133], v[58:59], v[226:227], v[132:133]
	ds_read_b128 v[56:59], v255 offset:80
	global_load_dwordx4 v[28:31], v248, s[16:17] offset:48
	s_waitcnt vmcnt(5)
	v_lshlrev_b32_e32 v224, 16, v32
	v_and_b32_e32 v225, 0xffff0000, v32
	v_lshlrev_b32_e32 v226, 16, v33
	v_and_b32_e32 v227, 0xffff0000, v33
	s_waitcnt lgkmcnt(3)
	v_pk_fma_f32 v[126:127], v[60:61], v[224:225], v[126:127]
	v_pk_fma_f32 v[128:129], v[62:63], v[226:227], v[128:129]
	ds_read_b128 v[60:63], v255 offset:1792
	v_lshlrev_b32_e32 v224, 16, v34
	v_and_b32_e32 v225, 0xffff0000, v34
	v_lshlrev_b32_e32 v226, 16, v35
	v_and_b32_e32 v227, 0xffff0000, v35
	s_waitcnt lgkmcnt(3)
	v_pk_fma_f32 v[130:131], v[220:221], v[224:225], v[130:131]
	v_pk_fma_f32 v[132:133], v[222:223], v[226:227], v[132:133]
	ds_read_b128 v[220:223], v255 offset:1808
	global_load_dwordx4 v[32:35], v249, s[16:17] offset:48
	v_pk_mul_f32 v[224:225], v[126:127], s[18:19] op_sel_hi:[1,0]
	v_pk_mul_f32 v[226:227], v[128:129], s[18:19] op_sel_hi:[1,0]
	v_pk_mul_f32 v[2:3], v[130:131], s[18:19] op_sel_hi:[1,0]
	v_pk_mul_f32 v[134:135], v[132:133], s[18:19] op_sel_hi:[1,0]
	v_exp_f32_e32 v224, v224
	v_exp_f32_e32 v225, v225
	v_exp_f32_e32 v226, v226
	v_exp_f32_e32 v227, v227
	v_exp_f32_e32 v2, v2
	v_exp_f32_e32 v3, v3
	v_exp_f32_e32 v134, v134
	v_exp_f32_e32 v135, v135
	v_pk_add_f32 v[224:225], v[224:225], 1.0 op_sel_hi:[1,0]
	v_pk_add_f32 v[226:227], v[226:227], 1.0 op_sel_hi:[1,0]
	v_pk_add_f32 v[2:3], v[2:3], 1.0 op_sel_hi:[1,0]
	v_pk_add_f32 v[134:135], v[134:135], 1.0 op_sel_hi:[1,0]
	v_rcp_f32_e32 v224, v224
	v_rcp_f32_e32 v225, v225
	v_rcp_f32_e32 v226, v226
	v_rcp_f32_e32 v227, v227
	v_rcp_f32_e32 v2, v2
	v_rcp_f32_e32 v3, v3
	v_rcp_f32_e32 v134, v134
	v_rcp_f32_e32 v135, v135
	v_pk_mul_f32 v[16:17], v[126:127], v[224:225]
	v_pk_mul_f32 v[18:19], v[128:129], v[226:227]
	v_pk_mul_f32 v[20:21], v[130:131], v[2:3]
	v_pk_mul_f32 v[22:23], v[132:133], v[134:135]
	v_pk_mul_f32 v[216:217], v[16:17], v[16:17]
	v_add_f32_e32 v218, v218, v216
	v_add_f32_e32 v218, v217, v218
	v_pk_mul_f32 v[216:217], v[18:19], v[18:19]
	v_add_f32_e32 v218, v218, v216
	v_add_f32_e32 v218, v217, v218
	v_pk_mul_f32 v[216:217], v[20:21], v[20:21]
	v_add_f32_e32 v218, v218, v216
	v_add_f32_e32 v218, v217, v218
	v_pk_mul_f32 v[216:217], v[22:23], v[22:23]
	v_add_f32_e32 v218, v218, v216
	v_add_f32_e32 v218, v217, v218
	s_cmp_lg_u32 s15, 0
	s_cbranch_scc1 .Lpb_sk_2
	s_waitcnt vmcnt(3)
	v_cndmask_b32_e64 v36, 0, v36, s[70:71]
	v_cndmask_b32_e64 v37, 0, v37, s[70:71]
	v_cndmask_b32_e64 v38, 0, v38, s[70:71]
	v_cndmask_b32_e64 v39, 0, v39, s[70:71]
	v_cndmask_b32_e64 v40, 0, v40, s[72:73]
	v_cndmask_b32_e64 v41, 0, v41, s[72:73]
	v_cndmask_b32_e64 v42, 0, v42, s[72:73]
	v_cndmask_b32_e64 v43, 0, v43, s[72:73]
	v_cndmask_b32_e64 v44, 0, v44, s[74:75]
	v_cndmask_b32_e64 v45, 0, v45, s[74:75]
	v_cndmask_b32_e64 v46, 0, v46, s[74:75]
	v_cndmask_b32_e64 v47, 0, v47, s[74:75]
.Lpb_sk_2:
	s_waitcnt vmcnt(5)
	v_lshlrev_b32_e32 v224, 16, v36
	v_and_b32_e32 v225, 0xffff0000, v36
	v_lshlrev_b32_e32 v226, 16, v37
	v_and_b32_e32 v227, 0xffff0000, v37
	s_waitcnt lgkmcnt(3)
	v_pk_fma_f32 v[126:127], v[48:49], v[224:225], 0 op_sel_hi:[1,1,0]
	v_pk_fma_f32 v[128:129], v[50:51], v[226:227], 0 op_sel_hi:[1,1,0]
	ds_read_b128 v[48:51], v255 offset:3520
	v_lshlrev_b32_e32 v224, 16, v38
	v_and_b32_e32 v225, 0xffff0000, v38
	v_lshlrev_b32_e32 v226, 16, v39
	v_and_b32_e32 v227, 0xffff0000, v39
	s_waitcnt lgkmcnt(3)
	v_pk_fma_f32 v[130:131], v[56:57], v[224:225], 0 op_sel_hi:[1,1,0]
	v_pk_fma_f32 v[132:133], v[58:59], v[226:227], 0 op_sel_hi:[1,1,0]
	ds_read_b128 v[56:59], v255 offset:3536
	global_load_dwordx4 v[36:39], v253, s[16:17] offset:48
	s_waitcnt vmcnt(5)
	v_lshlrev_b32_e32 v224, 16, v40
	v_and_b32_e32 v225, 0xffff0000, v40
	v_lshlrev_b32_e32 v226, 16, v41
	v_and_b32_e32 v227, 0xffff0000, v41
	s_waitcnt lgkmcnt(3)
	v_pk_fma_f32 v[126:127], v[60:61], v[224:225], v[126:127]
	v_pk_fma_f32 v[128:129], v[62:63], v[226:227], v[128:129]
	ds_read_b128 v[60:63], v255 offset:5248
	v_lshlrev_b32_e32 v224, 16, v42
	v_and_b32_e32 v225, 0xffff0000, v42
	v_lshlrev_b32_e32 v226, 16, v43
	v_and_b32_e32 v227, 0xffff0000, v43
	s_waitcnt lgkmcnt(3)
	v_pk_fma_f32 v[130:131], v[220:221], v[224:225], v[130:131]
	v_pk_fma_f32 v[132:133], v[222:223], v[226:227], v[132:133]
	ds_read_b128 v[220:223], v255 offset:5264
	global_load_dwordx4 v[40:43], v254, s[16:17] offset:48
	s_waitcnt vmcnt(5)
	v_lshlrev_b32_e32 v224, 16, v44
	v_and_b32_e32 v225, 0xffff0000, v44
	v_lshlrev_b32_e32 v226, 16, v45
	v_and_b32_e32 v227, 0xffff0000, v45
	s_waitcnt lgkmcnt(3)
	v_pk_fma_f32 v[126:127], v[48:49], v[224:225], v[126:127]
	v_pk_fma_f32 v[128:129], v[50:51], v[226:227], v[128:129]
	ds_read_b128 v[48:51], v255 offset:96
	v_lshlrev_b32_e32 v224, 16, v46
	v_and_b32_e32 v225, 0xffff0000, v46
	v_lshlrev_b32_e32 v226, 16, v47
	v_and_b32_e32 v227, 0xffff0000, v47
	s_waitcnt lgkmcnt(3)
	v_pk_fma_f32 v[130:131], v[56:57], v[224:225], v[130:131]
	v_pk_fma_f32 v[132:133], v[58:59], v[226:227], v[132:133]
	ds_read_b128 v[56:59], v255 offset:112
	global_load_dwordx4 v[44:47], v248, s[16:17] offset:1024
	s_waitcnt vmcnt(5)
	v_lshlrev_b32_e32 v224, 16, v52
	v_and_b32_e32 v225, 0xffff0000, v52
	v_lshlrev_b32_e32 v226, 16, v53
	v_and_b32_e32 v227, 0xffff0000, v53
	s_waitcnt lgkmcnt(3)
	v_pk_fma_f32 v[126:127], v[60:61], v[224:225], v[126:127]
	v_pk_fma_f32 v[128:129], v[62:63], v[226:227], v[128:129]
	ds_read_b128 v[60:63], v255 offset:1824
	v_lshlrev_b32_e32 v224, 16, v54
	v_and_b32_e32 v225, 0xffff0000, v54
	v_lshlrev_b32_e32 v226, 16, v55
	v_and_b32_e32 v227, 0xffff0000, v55
	s_waitcnt lgkmcnt(3)
	v_pk_fma_f32 v[130:131], v[220:221], v[224:225], v[130:131]
	v_pk_fma_f32 v[132:133], v[222:223], v[226:227], v[132:133]
	ds_read_b128 v[220:223], v255 offset:1840
	global_load_dwordx4 v[52:55], v249, s[16:17] offset:1024
	v_pk_mul_f32 v[224:225], v[126:127], s[18:19] op_sel_hi:[1,0]
	v_pk_mul_f32 v[226:227], v[128:129], s[18:19] op_sel_hi:[1,0]
	v_pk_mul_f32 v[2:3], v[130:131], s[18:19] op_sel_hi:[1,0]
	v_pk_mul_f32 v[134:135], v[132:133], s[18:19] op_sel_hi:[1,0]
	v_exp_f32_e32 v224, v224
	v_exp_f32_e32 v225, v225
	v_exp_f32_e32 v226, v226
	v_exp_f32_e32 v227, v227
	v_exp_f32_e32 v2, v2
	v_exp_f32_e32 v3, v3
	v_exp_f32_e32 v134, v134
	v_exp_f32_e32 v135, v135
	v_pk_add_f32 v[224:225], v[224:225], 1.0 op_sel_hi:[1,0]
	v_pk_add_f32 v[226:227], v[226:227], 1.0 op_sel_hi:[1,0]
	v_pk_add_f32 v[2:3], v[2:3], 1.0 op_sel_hi:[1,0]
	v_pk_add_f32 v[134:135], v[134:135], 1.0 op_sel_hi:[1,0]
	v_rcp_f32_e32 v224, v224
	v_rcp_f32_e32 v225, v225
	v_rcp_f32_e32 v226, v226
	v_rcp_f32_e32 v227, v227
	v_rcp_f32_e32 v2, v2
	v_rcp_f32_e32 v3, v3
	v_rcp_f32_e32 v134, v134
	v_rcp_f32_e32 v135, v135
	v_pk_mul_f32 v[24:25], v[126:127], v[224:225]
	v_pk_mul_f32 v[26:27], v[128:129], v[226:227]
	v_pk_mul_f32 v[64:65], v[130:131], v[2:3]
	v_pk_mul_f32 v[66:67], v[132:133], v[134:135]
	v_pk_mul_f32 v[216:217], v[24:25], v[24:25]
	v_add_f32_e32 v218, v218, v216
	v_add_f32_e32 v218, v217, v218
	v_pk_mul_f32 v[216:217], v[26:27], v[26:27]
	v_add_f32_e32 v218, v218, v216
	v_add_f32_e32 v218, v217, v218
	v_pk_mul_f32 v[216:217], v[64:65], v[64:65]
	v_add_f32_e32 v218, v218, v216
	v_add_f32_e32 v218, v217, v218
	v_pk_mul_f32 v[216:217], v[66:67], v[66:67]
	v_add_f32_e32 v218, v218, v216
	v_add_f32_e32 v218, v217, v218
	s_cmp_lg_u32 s15, 0
	s_cbranch_scc1 .Lpb_sk_3
	s_waitcnt vmcnt(3)
	v_cndmask_b32_e64 v28, 0, v28, s[70:71]
	v_cndmask_b32_e64 v29, 0, v29, s[70:71]
	v_cndmask_b32_e64 v30, 0, v30, s[70:71]
	v_cndmask_b32_e64 v31, 0, v31, s[70:71]
	v_cndmask_b32_e64 v32, 0, v32, s[72:73]
	v_cndmask_b32_e64 v33, 0, v33, s[72:73]
	v_cndmask_b32_e64 v34, 0, v34, s[72:73]
	v_cndmask_b32_e64 v35, 0, v35, s[72:73]
	v_cndmask_b32_e64 v36, 0, v36, s[74:75]
	v_cndmask_b32_e64 v37, 0, v37, s[74:75]
	v_cndmask_b32_e64 v38, 0, v38, s[74:75]
	v_cndmask_b32_e64 v39, 0, v39, s[74:75]
.Lpb_sk_3:
	s_waitcnt vmcnt(5)
	v_lshlrev_b32_e32 v224, 16, v28
	v_and_b32_e32 v225, 0xffff0000, v28
	v_lshlrev_b32_e32 v226, 16, v29
	v_and_b32_e32 v227, 0xffff0000, v29
	s_waitcnt lgkmcnt(3)
	v_pk_fma_f32 v[126:127], v[48:49], v[224:225], 0 op_sel_hi:[1,1,0]
	v_pk_fma_f32 v[128:129], v[50:51], v[226:227], 0 op_sel_hi:[1,1,0]
	ds_read_b128 v[48:51], v255 offset:3552
	v_lshlrev_b32_e32 v224, 16, v30
	v_and_b32_e32 v225, 0xffff0000, v30
	v_lshlrev_b32_e32 v226, 16, v31
	v_and_b32_e32 v227, 0xffff0000, v31
	s_waitcnt lgkmcnt(3)
	v_pk_fma_f32 v[130:131], v[56:57], v[224:225], 0 op_sel_hi:[1,1,0]
	v_pk_fma_f32 v[132:133], v[58:59], v[226:227], 0 op_sel_hi:[1,1,0]
	ds_read_b128 v[56:59], v255 offset:3568
	global_load_dwordx4 v[28:31], v253, s[16:17] offset:1024
	s_waitcnt vmcnt(5)
	v_lshlrev_b32_e32 v224, 16, v32
	v_and_b32_e32 v225, 0xffff0000, v32
	v_lshlrev_b32_e32 v226, 16, v33
	v_and_b32_e32 v227, 0xffff0000, v33
	s_waitcnt lgkmcnt(3)
	v_pk_fma_f32 v[126:127], v[60:61], v[224:225], v[126:127]
	v_pk_fma_f32 v[128:129], v[62:63], v[226:227], v[128:129]
	ds_read_b128 v[60:63], v255 offset:5280
	v_lshlrev_b32_e32 v224, 16, v34
	v_and_b32_e32 v225, 0xffff0000, v34
	v_lshlrev_b32_e32 v226, 16, v35
	v_and_b32_e32 v227, 0xffff0000, v35
	s_waitcnt lgkmcnt(3)
	v_pk_fma_f32 v[130:131], v[220:221], v[224:225], v[130:131]
	v_pk_fma_f32 v[132:133], v[222:223], v[226:227], v[132:133]
	ds_read_b128 v[220:223], v255 offset:5296
	global_load_dwordx4 v[32:35], v254, s[16:17] offset:1024
	s_waitcnt vmcnt(5)
	v_lshlrev_b32_e32 v224, 16, v36
	v_and_b32_e32 v225, 0xffff0000, v36
	v_lshlrev_b32_e32 v226, 16, v37
	v_and_b32_e32 v227, 0xffff0000, v37
	s_waitcnt lgkmcnt(3)
	v_pk_fma_f32 v[126:127], v[48:49], v[224:225], v[126:127]
	v_pk_fma_f32 v[128:129], v[50:51], v[226:227], v[128:129]
	ds_read_b128 v[48:51], v255 offset:576
	v_lshlrev_b32_e32 v224, 16, v38
	v_and_b32_e32 v225, 0xffff0000, v38
	v_lshlrev_b32_e32 v226, 16, v39
	v_and_b32_e32 v227, 0xffff0000, v39
	s_waitcnt lgkmcnt(3)
	v_pk_fma_f32 v[130:131], v[56:57], v[224:225], v[130:131]
	v_pk_fma_f32 v[132:133], v[58:59], v[226:227], v[132:133]
	ds_read_b128 v[56:59], v255 offset:592
	global_load_dwordx4 v[36:39], v248, s[16:17] offset:1040
	s_waitcnt vmcnt(5)
	v_lshlrev_b32_e32 v224, 16, v40
	v_and_b32_e32 v225, 0xffff0000, v40
	v_lshlrev_b32_e32 v226, 16, v41
	v_and_b32_e32 v227, 0xffff0000, v41
	s_waitcnt lgkmcnt(3)
	v_pk_fma_f32 v[126:127], v[60:61], v[224:225], v[126:127]
	v_pk_fma_f32 v[128:129], v[62:63], v[226:227], v[128:129]
	ds_read_b128 v[60:63], v255 offset:2304
	v_lshlrev_b32_e32 v224, 16, v42
	v_and_b32_e32 v225, 0xffff0000, v42
	v_lshlrev_b32_e32 v226, 16, v43
	v_and_b32_e32 v227, 0xffff0000, v43
	s_waitcnt lgkmcnt(3)
	v_pk_fma_f32 v[130:131], v[220:221], v[224:225], v[130:131]
	v_pk_fma_f32 v[132:133], v[222:223], v[226:227], v[132:133]
	ds_read_b128 v[220:223], v255 offset:2320
	global_load_dwordx4 v[40:43], v249, s[16:17] offset:1040
	v_pk_mul_f32 v[224:225], v[126:127], s[18:19] op_sel_hi:[1,0]
	v_pk_mul_f32 v[226:227], v[128:129], s[18:19] op_sel_hi:[1,0]
	v_pk_mul_f32 v[2:3], v[130:131], s[18:19] op_sel_hi:[1,0]
	v_pk_mul_f32 v[134:135], v[132:133], s[18:19] op_sel_hi:[1,0]
	v_exp_f32_e32 v224, v224
	v_exp_f32_e32 v225, v225
	v_exp_f32_e32 v226, v226
	v_exp_f32_e32 v227, v227
	v_exp_f32_e32 v2, v2
	v_exp_f32_e32 v3, v3
	v_exp_f32_e32 v134, v134
	v_exp_f32_e32 v135, v135
	v_pk_add_f32 v[224:225], v[224:225], 1.0 op_sel_hi:[1,0]
	v_pk_add_f32 v[226:227], v[226:227], 1.0 op_sel_hi:[1,0]
	v_pk_add_f32 v[2:3], v[2:3], 1.0 op_sel_hi:[1,0]
	v_pk_add_f32 v[134:135], v[134:135], 1.0 op_sel_hi:[1,0]
	v_rcp_f32_e32 v224, v224
	v_rcp_f32_e32 v225, v225
	v_rcp_f32_e32 v226, v226
	v_rcp_f32_e32 v227, v227
	v_rcp_f32_e32 v2, v2
	v_rcp_f32_e32 v3, v3
	v_rcp_f32_e32 v134, v134
	v_rcp_f32_e32 v135, v135
	v_pk_mul_f32 v[68:69], v[126:127], v[224:225]
	v_pk_mul_f32 v[70:71], v[128:129], v[226:227]
	v_pk_mul_f32 v[122:123], v[130:131], v[2:3]
	v_pk_mul_f32 v[124:125], v[132:133], v[134:135]
	v_pk_mul_f32 v[216:217], v[68:69], v[68:69]
	v_add_f32_e32 v218, v218, v216
	v_add_f32_e32 v218, v217, v218
	v_pk_mul_f32 v[216:217], v[70:71], v[70:71]
	v_add_f32_e32 v218, v218, v216
	v_add_f32_e32 v218, v217, v218
	v_pk_mul_f32 v[216:217], v[122:123], v[122:123]
	v_add_f32_e32 v218, v218, v216
	v_add_f32_e32 v218, v217, v218
	v_pk_mul_f32 v[216:217], v[124:125], v[124:125]
	v_add_f32_e32 v218, v218, v216
	v_add_f32_e32 v218, v217, v218
	s_nop 1
	v_add_f32_dpp v119, v218, v218 quad_perm:[1,0,3,2] row_mask:0xf bank_mask:0xf
	s_nop 1
	v_add_f32_dpp v216, v119, v119 quad_perm:[2,3,0,1] row_mask:0xf bank_mask:0xf
	v_add_f32_e32 v216, 0x358637bd, v216
	v_mul_f32_e32 v119, 0x4b800000, v216
	v_cmp_gt_f32_e32 vcc, 0x800000, v216
	s_nop 1
	v_cndmask_b32_e32 v216, v216, v119, vcc
	v_rsq_f32_e32 v216, v216
	s_nop 0
	v_mul_f32_e32 v119, 0x45800000, v216
	v_cndmask_b32_e32 v216, v216, v119, vcc
	v_mul_f32_e32 v216, 0x3db504f3, v216
	v_pk_mul_f32 v[8:9], v[8:9], v[216:217] op_sel_hi:[1,0]
	v_pk_mul_f32 v[10:11], v[10:11], v[216:217] op_sel_hi:[1,0]
	v_pk_mul_f32 v[12:13], v[12:13], v[216:217] op_sel_hi:[1,0]
	v_pk_mul_f32 v[14:15], v[14:15], v[216:217] op_sel_hi:[1,0]
	v_pk_mul_f32 v[16:17], v[16:17], v[216:217] op_sel_hi:[1,0]
	v_pk_mul_f32 v[18:19], v[18:19], v[216:217] op_sel_hi:[1,0]
	v_pk_mul_f32 v[20:21], v[20:21], v[216:217] op_sel_hi:[1,0]
	v_pk_mul_f32 v[22:23], v[22:23], v[216:217] op_sel_hi:[1,0]
	v_pk_mul_f32 v[24:25], v[24:25], v[216:217] op_sel_hi:[1,0]
	v_pk_mul_f32 v[26:27], v[26:27], v[216:217] op_sel_hi:[1,0]
	v_pk_mul_f32 v[64:65], v[64:65], v[216:217] op_sel_hi:[1,0]
	v_pk_mul_f32 v[66:67], v[66:67], v[216:217] op_sel_hi:[1,0]
	v_pk_mul_f32 v[68:69], v[68:69], v[216:217] op_sel_hi:[1,0]
	v_pk_mul_f32 v[70:71], v[70:71], v[216:217] op_sel_hi:[1,0]
	v_pk_mul_f32 v[122:123], v[122:123], v[216:217] op_sel_hi:[1,0]
	v_pk_mul_f32 v[124:125], v[124:125], v[216:217] op_sel_hi:[1,0]
	v_mov_b32_e32 v218, 0
	v_cvt_pk_bf16_f32 v224, v8, v9
	v_cvt_pk_bf16_f32 v225, v10, v11
	v_cvt_pk_bf16_f32 v226, v12, v13
	v_cvt_pk_bf16_f32 v227, v14, v15
	v_xor_b32_e32 v119, 0, v113
	v_lshl_add_u32 v119, v119, 4, v111
	ds_write_b128 v119, v[224:227] offset:16384
	v_pk_mul_f32 v[2:3], v[230:231], v[8:9] op_sel_hi:[0,1]
	v_pk_mul_f32 v[134:135], v[230:231], v[10:11] op_sel_hi:[0,1]
	v_cvt_pk_bf16_f32 v224, v2, v3
	v_cvt_pk_bf16_f32 v225, v134, v135
	v_pk_mul_f32 v[2:3], v[230:231], v[12:13] op_sel_hi:[0,1]
	v_pk_mul_f32 v[134:135], v[230:231], v[14:15] op_sel_hi:[0,1]
	v_cvt_pk_bf16_f32 v226, v2, v3
	v_cvt_pk_bf16_f32 v227, v134, v135
	global_store_dwordx4 v117, v[224:227], s[92:93] offset:0
	s_nop 1
	v_cvt_pk_bf16_f32 v224, v16, v17
	v_cvt_pk_bf16_f32 v225, v18, v19
	v_cvt_pk_bf16_f32 v226, v20, v21
	v_cvt_pk_bf16_f32 v227, v22, v23
	v_xor_b32_e32 v119, 1, v113
	v_lshl_add_u32 v119, v119, 4, v111
	ds_write_b128 v119, v[224:227] offset:16384
	v_pk_mul_f32 v[2:3], v[230:231], v[16:17] op_sel_hi:[0,1]
	v_pk_mul_f32 v[134:135], v[230:231], v[18:19] op_sel_hi:[0,1]
	v_cvt_pk_bf16_f32 v224, v2, v3
	v_cvt_pk_bf16_f32 v225, v134, v135
	v_pk_mul_f32 v[2:3], v[230:231], v[20:21] op_sel_hi:[0,1]
	v_pk_mul_f32 v[134:135], v[230:231], v[22:23] op_sel_hi:[0,1]
	v_cvt_pk_bf16_f32 v226, v2, v3
	v_cvt_pk_bf16_f32 v227, v134, v135
	global_store_dwordx4 v117, v[224:227], s[92:93] offset:16
	s_nop 1
	v_cvt_pk_bf16_f32 v224, v24, v25
	v_cvt_pk_bf16_f32 v225, v26, v27
	v_cvt_pk_bf16_f32 v226, v64, v65
	v_cvt_pk_bf16_f32 v227, v66, v67
	v_xor_b32_e32 v119, 2, v113
	v_lshl_add_u32 v119, v119, 4, v111
	ds_write_b128 v119, v[224:227] offset:16384
	v_pk_mul_f32 v[2:3], v[230:231], v[24:25] op_sel_hi:[0,1]
	v_pk_mul_f32 v[134:135], v[230:231], v[26:27] op_sel_hi:[0,1]
	v_cvt_pk_bf16_f32 v224, v2, v3
	v_cvt_pk_bf16_f32 v225, v134, v135
	v_pk_mul_f32 v[2:3], v[230:231], v[64:65] op_sel_hi:[0,1]
	v_pk_mul_f32 v[134:135], v[230:231], v[66:67] op_sel_hi:[0,1]
	v_cvt_pk_bf16_f32 v226, v2, v3
	v_cvt_pk_bf16_f32 v227, v134, v135
	global_store_dwordx4 v117, v[224:227], s[92:93] offset:32
	s_nop 1
	v_cvt_pk_bf16_f32 v224, v68, v69
	v_cvt_pk_bf16_f32 v225, v70, v71
	v_cvt_pk_bf16_f32 v226, v122, v123
	v_cvt_pk_bf16_f32 v227, v124, v125
	v_xor_b32_e32 v119, 3, v113
	v_lshl_add_u32 v119, v119, 4, v111
	ds_write_b128 v119, v[224:227] offset:16384
	v_pk_mul_f32 v[2:3], v[230:231], v[68:69] op_sel_hi:[0,1]
	v_pk_mul_f32 v[134:135], v[230:231], v[70:71] op_sel_hi:[0,1]
	v_cvt_pk_bf16_f32 v224, v2, v3
	v_cvt_pk_bf16_f32 v225, v134, v135
	v_pk_mul_f32 v[2:3], v[230:231], v[122:123] op_sel_hi:[0,1]
	v_pk_mul_f32 v[134:135], v[230:231], v[124:125] op_sel_hi:[0,1]
	v_cvt_pk_bf16_f32 v226, v2, v3
	v_cvt_pk_bf16_f32 v227, v134, v135
	global_store_dwordx4 v117, v[224:227], s[92:93] offset:48
	s_nop 1
	s_cmp_lg_u32 s15, 0
	s_cbranch_scc1 .Lpb_sk_4
	s_waitcnt vmcnt(7)
	v_cndmask_b32_e64 v44, 0, v44, s[70:71]
	v_cndmask_b32_e64 v45, 0, v45, s[70:71]
	v_cndmask_b32_e64 v46, 0, v46, s[70:71]
	v_cndmask_b32_e64 v47, 0, v47, s[70:71]
	v_cndmask_b32_e64 v52, 0, v52, s[72:73]
	v_cndmask_b32_e64 v53, 0, v53, s[72:73]
	v_cndmask_b32_e64 v54, 0, v54, s[72:73]
	v_cndmask_b32_e64 v55, 0, v55, s[72:73]
	v_cndmask_b32_e64 v28, 0, v28, s[74:75]
	v_cndmask_b32_e64 v29, 0, v29, s[74:75]
	v_cndmask_b32_e64 v30, 0, v30, s[74:75]
	v_cndmask_b32_e64 v31, 0, v31, s[74:75]
.Lpb_sk_4:
	s_waitcnt vmcnt(9)
	v_lshlrev_b32_e32 v224, 16, v44
	v_and_b32_e32 v225, 0xffff0000, v44
	v_lshlrev_b32_e32 v226, 16, v45
	v_and_b32_e32 v227, 0xffff0000, v45
	s_waitcnt lgkmcnt(7)
	v_pk_fma_f32 v[126:127], v[48:49], v[224:225], 0 op_sel_hi:[1,1,0]
	v_pk_fma_f32 v[128:129], v[50:51], v[226:227], 0 op_sel_hi:[1,1,0]
	ds_read_b128 v[48:51], v255 offset:4032
	v_lshlrev_b32_e32 v224, 16, v46
	v_and_b32_e32 v225, 0xffff0000, v46
	v_lshlrev_b32_e32 v226, 16, v47
	v_and_b32_e32 v227, 0xffff0000, v47
	s_waitcnt lgkmcnt(7)
	v_pk_fma_f32 v[130:131], v[56:57], v[224:225], 0 op_sel_hi:[1,1,0]
	v_pk_fma_f32 v[132:133], v[58:59], v[226:227], 0 op_sel_hi:[1,1,0]
	ds_read_b128 v[56:59], v255 offset:4048
	global_load_dwordx4 v[44:47], v253, s[16:17] offset:1040
	s_waitcnt vmcnt(9)
	v_lshlrev_b32_e32 v224, 16, v52
	v_and_b32_e32 v225, 0xffff0000, v52
	v_lshlrev_b32_e32 v226, 16, v53
	v_and_b32_e32 v227, 0xffff0000, v53
	s_waitcnt lgkmcnt(7)
	v_pk_fma_f32 v[126:127], v[60:61], v[224:225], v[126:127]
	v_pk_fma_f32 v[128:129], v[62:63], v[226:227], v[128:129]
	ds_read_b128 v[60:63], v255 offset:5760
	v_lshlrev_b32_e32 v224, 16, v54
	v_and_b32_e32 v225, 0xffff0000, v54
	v_lshlrev_b32_e32 v226, 16, v55
	v_and_b32_e32 v227, 0xffff0000, v55
	s_waitcnt lgkmcnt(7)
	v_pk_fma_f32 v[130:131], v[220:221], v[224:225], v[130:131]
	v_pk_fma_f32 v[132:133], v[222:223], v[226:227], v[132:133]
	ds_read_b128 v[220:223], v255 offset:5776
	global_load_dwordx4 v[52:55], v254, s[16:17] offset:1040
	s_waitcnt vmcnt(9)
	v_lshlrev_b32_e32 v224, 16, v28
	v_and_b32_e32 v225, 0xffff0000, v28
	v_lshlrev_b32_e32 v226, 16, v29
	v_and_b32_e32 v227, 0xffff0000, v29
	s_waitcnt lgkmcnt(3)
	v_pk_fma_f32 v[126:127], v[48:49], v[224:225], v[126:127]
	v_pk_fma_f32 v[128:129], v[50:51], v[226:227], v[128:129]
	ds_read_b128 v[48:51], v255 offset:608
	v_lshlrev_b32_e32 v224, 16, v30
	v_and_b32_e32 v225, 0xffff0000, v30
	v_lshlrev_b32_e32 v226, 16, v31
	v_and_b32_e32 v227, 0xffff0000, v31
	s_waitcnt lgkmcnt(3)
	v_pk_fma_f32 v[130:131], v[56:57], v[224:225], v[130:131]
	v_pk_fma_f32 v[132:133], v[58:59], v[226:227], v[132:133]
	ds_read_b128 v[56:59], v255 offset:624
	global_load_dwordx4 v[28:31], v248, s[16:17] offset:1056
	s_waitcnt vmcnt(9)
	v_lshlrev_b32_e32 v224, 16, v32
	v_and_b32_e32 v225, 0xffff0000, v32
	v_lshlrev_b32_e32 v226, 16, v33
	v_and_b32_e32 v227, 0xffff0000, v33
	s_waitcnt lgkmcnt(3)
	v_pk_fma_f32 v[126:127], v[60:61], v[224:225], v[126:127]
	v_pk_fma_f32 v[128:129], v[62:63], v[226:227], v[128:129]
	ds_read_b128 v[60:63], v255 offset:2336
	v_lshlrev_b32_e32 v224, 16, v34
	v_and_b32_e32 v225, 0xffff0000, v34
	v_lshlrev_b32_e32 v226, 16, v35
	v_and_b32_e32 v227, 0xffff0000, v35
	s_waitcnt lgkmcnt(3)
	v_pk_fma_f32 v[130:131], v[220:221], v[224:225], v[130:131]
	v_pk_fma_f32 v[132:133], v[222:223], v[226:227], v[132:133]
	ds_read_b128 v[220:223], v255 offset:2352
	global_load_dwordx4 v[32:35], v249, s[16:17] offset:1056
	v_pk_mul_f32 v[224:225], v[126:127], s[18:19] op_sel_hi:[1,0]
	v_pk_mul_f32 v[226:227], v[128:129], s[18:19] op_sel_hi:[1,0]
	v_pk_mul_f32 v[2:3], v[130:131], s[18:19] op_sel_hi:[1,0]
	v_pk_mul_f32 v[134:135], v[132:133], s[18:19] op_sel_hi:[1,0]
	v_exp_f32_e32 v224, v224
	v_exp_f32_e32 v225, v225
	v_exp_f32_e32 v226, v226
	v_exp_f32_e32 v227, v227
	v_exp_f32_e32 v2, v2
	v_exp_f32_e32 v3, v3
	v_exp_f32_e32 v134, v134
	v_exp_f32_e32 v135, v135
	v_pk_add_f32 v[224:225], v[224:225], 1.0 op_sel_hi:[1,0]
	v_pk_add_f32 v[226:227], v[226:227], 1.0 op_sel_hi:[1,0]
	v_pk_add_f32 v[2:3], v[2:3], 1.0 op_sel_hi:[1,0]
	v_pk_add_f32 v[134:135], v[134:135], 1.0 op_sel_hi:[1,0]
	v_rcp_f32_e32 v224, v224
	v_rcp_f32_e32 v225, v225
	v_rcp_f32_e32 v226, v226
	v_rcp_f32_e32 v227, v227
	v_rcp_f32_e32 v2, v2
	v_rcp_f32_e32 v3, v3
	v_rcp_f32_e32 v134, v134
	v_rcp_f32_e32 v135, v135
	v_pk_mul_f32 v[8:9], v[126:127], v[224:225]
	v_pk_mul_f32 v[10:11], v[128:129], v[226:227]
	v_pk_mul_f32 v[12:13], v[130:131], v[2:3]
	v_pk_mul_f32 v[14:15], v[132:133], v[134:135]
	v_pk_mul_f32 v[216:217], v[8:9], v[8:9]
	v_add_f32_e32 v218, v218, v216
	v_add_f32_e32 v218, v217, v218
	v_pk_mul_f32 v[216:217], v[10:11], v[10:11]
	v_add_f32_e32 v218, v218, v216
	v_add_f32_e32 v218, v217, v218
	v_pk_mul_f32 v[216:217], v[12:13], v[12:13]
	v_add_f32_e32 v218, v218, v216
	v_add_f32_e32 v218, v217, v218
	v_pk_mul_f32 v[216:217], v[14:15], v[14:15]
	v_add_f32_e32 v218, v218, v216
	v_add_f32_e32 v218, v217, v218
	s_cmp_lg_u32 s15, 0
	s_cbranch_scc1 .Lpb_sk_5
	s_waitcnt vmcnt(3)
	v_cndmask_b32_e64 v36, 0, v36, s[70:71]
	v_cndmask_b32_e64 v37, 0, v37, s[70:71]
	v_cndmask_b32_e64 v38, 0, v38, s[70:71]
	v_cndmask_b32_e64 v39, 0, v39, s[70:71]
	v_cndmask_b32_e64 v40, 0, v40, s[72:73]
	v_cndmask_b32_e64 v41, 0, v41, s[72:73]
	v_cndmask_b32_e64 v42, 0, v42, s[72:73]
	v_cndmask_b32_e64 v43, 0, v43, s[72:73]
	v_cndmask_b32_e64 v44, 0, v44, s[74:75]
	v_cndmask_b32_e64 v45, 0, v45, s[74:75]
	v_cndmask_b32_e64 v46, 0, v46, s[74:75]
	v_cndmask_b32_e64 v47, 0, v47, s[74:75]
.Lpb_sk_5:
	s_waitcnt vmcnt(9)
	v_lshlrev_b32_e32 v224, 16, v36
	v_and_b32_e32 v225, 0xffff0000, v36
	v_lshlrev_b32_e32 v226, 16, v37
	v_and_b32_e32 v227, 0xffff0000, v37
	s_waitcnt lgkmcnt(3)
	v_pk_fma_f32 v[126:127], v[48:49], v[224:225], 0 op_sel_hi:[1,1,0]
	v_pk_fma_f32 v[128:129], v[50:51], v[226:227], 0 op_sel_hi:[1,1,0]
	ds_read_b128 v[48:51], v255 offset:4064
	v_lshlrev_b32_e32 v224, 16, v38
	v_and_b32_e32 v225, 0xffff0000, v38
	v_lshlrev_b32_e32 v226, 16, v39
	v_and_b32_e32 v227, 0xffff0000, v39
	s_waitcnt lgkmcnt(3)
	v_pk_fma_f32 v[130:131], v[56:57], v[224:225], 0 op_sel_hi:[1,1,0]
	v_pk_fma_f32 v[132:133], v[58:59], v[226:227], 0 op_sel_hi:[1,1,0]
	ds_read_b128 v[56:59], v255 offset:4080
	global_load_dwordx4 v[36:39], v253, s[16:17] offset:1056
	s_waitcnt vmcnt(9)
	v_lshlrev_b32_e32 v224, 16, v40
	v_and_b32_e32 v225, 0xffff0000, v40
	v_lshlrev_b32_e32 v226, 16, v41
	v_and_b32_e32 v227, 0xffff0000, v41
	s_waitcnt lgkmcnt(3)
	v_pk_fma_f32 v[126:127], v[60:61], v[224:225], v[126:127]
	v_pk_fma_f32 v[128:129], v[62:63], v[226:227], v[128:129]
	ds_read_b128 v[60:63], v255 offset:5792
	v_lshlrev_b32_e32 v224, 16, v42
	v_and_b32_e32 v225, 0xffff0000, v42
	v_lshlrev_b32_e32 v226, 16, v43
	v_and_b32_e32 v227, 0xffff0000, v43
	s_waitcnt lgkmcnt(3)
	v_pk_fma_f32 v[130:131], v[220:221], v[224:225], v[130:131]
	v_pk_fma_f32 v[132:133], v[222:223], v[226:227], v[132:133]
	ds_read_b128 v[220:223], v255 offset:5808
	global_load_dwordx4 v[40:43], v254, s[16:17] offset:1056
	s_waitcnt vmcnt(5)
	v_lshlrev_b32_e32 v224, 16, v44
	v_and_b32_e32 v225, 0xffff0000, v44
	v_lshlrev_b32_e32 v226, 16, v45
	v_and_b32_e32 v227, 0xffff0000, v45
	s_waitcnt lgkmcnt(3)
	v_pk_fma_f32 v[126:127], v[48:49], v[224:225], v[126:127]
	v_pk_fma_f32 v[128:129], v[50:51], v[226:227], v[128:129]
	ds_read_b128 v[48:51], v255 offset:640
	v_lshlrev_b32_e32 v224, 16, v46
	v_and_b32_e32 v225, 0xffff0000, v46
	v_lshlrev_b32_e32 v226, 16, v47
	v_and_b32_e32 v227, 0xffff0000, v47
	s_waitcnt lgkmcnt(3)
	v_pk_fma_f32 v[130:131], v[56:57], v[224:225], v[130:131]
	v_pk_fma_f32 v[132:133], v[58:59], v[226:227], v[132:133]
	ds_read_b128 v[56:59], v255 offset:656
	global_load_dwordx4 v[44:47], v248, s[16:17] offset:1072
	s_waitcnt vmcnt(5)
	v_lshlrev_b32_e32 v224, 16, v52
	v_and_b32_e32 v225, 0xffff0000, v52
	v_lshlrev_b32_e32 v226, 16, v53
	v_and_b32_e32 v227, 0xffff0000, v53
	s_waitcnt lgkmcnt(3)
	v_pk_fma_f32 v[126:127], v[60:61], v[224:225], v[126:127]
	v_pk_fma_f32 v[128:129], v[62:63], v[226:227], v[128:129]
	ds_read_b128 v[60:63], v255 offset:2368
	v_lshlrev_b32_e32 v224, 16, v54
	v_and_b32_e32 v225, 0xffff0000, v54
	v_lshlrev_b32_e32 v226, 16, v55
	v_and_b32_e32 v227, 0xffff0000, v55
	s_waitcnt lgkmcnt(3)
	v_pk_fma_f32 v[130:131], v[220:221], v[224:225], v[130:131]
	v_pk_fma_f32 v[132:133], v[222:223], v[226:227], v[132:133]
	ds_read_b128 v[220:223], v255 offset:2384
	global_load_dwordx4 v[52:55], v249, s[16:17] offset:1072
	v_pk_mul_f32 v[224:225], v[126:127], s[18:19] op_sel_hi:[1,0]
	v_pk_mul_f32 v[226:227], v[128:129], s[18:19] op_sel_hi:[1,0]
	v_pk_mul_f32 v[2:3], v[130:131], s[18:19] op_sel_hi:[1,0]
	v_pk_mul_f32 v[134:135], v[132:133], s[18:19] op_sel_hi:[1,0]
	v_exp_f32_e32 v224, v224
	v_exp_f32_e32 v225, v225
	v_exp_f32_e32 v226, v226
	v_exp_f32_e32 v227, v227
	v_exp_f32_e32 v2, v2
	v_exp_f32_e32 v3, v3
	v_exp_f32_e32 v134, v134
	v_exp_f32_e32 v135, v135
	v_pk_add_f32 v[224:225], v[224:225], 1.0 op_sel_hi:[1,0]
	v_pk_add_f32 v[226:227], v[226:227], 1.0 op_sel_hi:[1,0]
	v_pk_add_f32 v[2:3], v[2:3], 1.0 op_sel_hi:[1,0]
	v_pk_add_f32 v[134:135], v[134:135], 1.0 op_sel_hi:[1,0]
	v_rcp_f32_e32 v224, v224
	v_rcp_f32_e32 v225, v225
	v_rcp_f32_e32 v226, v226
	v_rcp_f32_e32 v227, v227
	v_rcp_f32_e32 v2, v2
	v_rcp_f32_e32 v3, v3
	v_rcp_f32_e32 v134, v134
	v_rcp_f32_e32 v135, v135
	v_pk_mul_f32 v[16:17], v[126:127], v[224:225]
	v_pk_mul_f32 v[18:19], v[128:129], v[226:227]
	v_pk_mul_f32 v[20:21], v[130:131], v[2:3]
	v_pk_mul_f32 v[22:23], v[132:133], v[134:135]
	v_pk_mul_f32 v[216:217], v[16:17], v[16:17]
	v_add_f32_e32 v218, v218, v216
	v_add_f32_e32 v218, v217, v218
	v_pk_mul_f32 v[216:217], v[18:19], v[18:19]
	v_add_f32_e32 v218, v218, v216
	v_add_f32_e32 v218, v217, v218
	v_pk_mul_f32 v[216:217], v[20:21], v[20:21]
	v_add_f32_e32 v218, v218, v216
	v_add_f32_e32 v218, v217, v218
	v_pk_mul_f32 v[216:217], v[22:23], v[22:23]
	v_add_f32_e32 v218, v218, v216
	v_add_f32_e32 v218, v217, v218
	s_cmp_lg_u32 s15, 0
	s_cbranch_scc1 .Lpb_sk_6
	s_waitcnt vmcnt(3)
	v_cndmask_b32_e64 v28, 0, v28, s[70:71]
	v_cndmask_b32_e64 v29, 0, v29, s[70:71]
	v_cndmask_b32_e64 v30, 0, v30, s[70:71]
	v_cndmask_b32_e64 v31, 0, v31, s[70:71]
	v_cndmask_b32_e64 v32, 0, v32, s[72:73]
	v_cndmask_b32_e64 v33, 0, v33, s[72:73]
	v_cndmask_b32_e64 v34, 0, v34, s[72:73]
	v_cndmask_b32_e64 v35, 0, v35, s[72:73]
	v_cndmask_b32_e64 v36, 0, v36, s[74:75]
	v_cndmask_b32_e64 v37, 0, v37, s[74:75]
	v_cndmask_b32_e64 v38, 0, v38, s[74:75]
	v_cndmask_b32_e64 v39, 0, v39, s[74:75]
.Lpb_sk_6:
	s_waitcnt vmcnt(5)
	v_lshlrev_b32_e32 v224, 16, v28
	v_and_b32_e32 v225, 0xffff0000, v28
	v_lshlrev_b32_e32 v226, 16, v29
	v_and_b32_e32 v227, 0xffff0000, v29
	s_waitcnt lgkmcnt(3)
	v_pk_fma_f32 v[126:127], v[48:49], v[224:225], 0 op_sel_hi:[1,1,0]
	v_pk_fma_f32 v[128:129], v[50:51], v[226:227], 0 op_sel_hi:[1,1,0]
	ds_read_b128 v[48:51], v255 offset:4096
	v_lshlrev_b32_e32 v224, 16, v30
	v_and_b32_e32 v225, 0xffff0000, v30
	v_lshlrev_b32_e32 v226, 16, v31
	v_and_b32_e32 v227, 0xffff0000, v31
	s_waitcnt lgkmcnt(3)
	v_pk_fma_f32 v[130:131], v[56:57], v[224:225], 0 op_sel_hi:[1,1,0]
	v_pk_fma_f32 v[132:133], v[58:59], v[226:227], 0 op_sel_hi:[1,1,0]
	ds_read_b128 v[56:59], v255 offset:4112
	global_load_dwordx4 v[28:31], v253, s[16:17] offset:1072
	s_waitcnt vmcnt(5)
	v_lshlrev_b32_e32 v224, 16, v32
	v_and_b32_e32 v225, 0xffff0000, v32
	v_lshlrev_b32_e32 v226, 16, v33
	v_and_b32_e32 v227, 0xffff0000, v33
	s_waitcnt lgkmcnt(3)
	v_pk_fma_f32 v[126:127], v[60:61], v[224:225], v[126:127]
	v_pk_fma_f32 v[128:129], v[62:63], v[226:227], v[128:129]
	ds_read_b128 v[60:63], v255 offset:5824
	v_lshlrev_b32_e32 v224, 16, v34
	v_and_b32_e32 v225, 0xffff0000, v34
	v_lshlrev_b32_e32 v226, 16, v35
	v_and_b32_e32 v227, 0xffff0000, v35
	s_waitcnt lgkmcnt(3)
	v_pk_fma_f32 v[130:131], v[220:221], v[224:225], v[130:131]
	v_pk_fma_f32 v[132:133], v[222:223], v[226:227], v[132:133]
	ds_read_b128 v[220:223], v255 offset:5840
	global_load_dwordx4 v[32:35], v254, s[16:17] offset:1072
	s_waitcnt vmcnt(5)
	v_lshlrev_b32_e32 v224, 16, v36
	v_and_b32_e32 v225, 0xffff0000, v36
	v_lshlrev_b32_e32 v226, 16, v37
	v_and_b32_e32 v227, 0xffff0000, v37
	s_waitcnt lgkmcnt(3)
	v_pk_fma_f32 v[126:127], v[48:49], v[224:225], v[126:127]
	v_pk_fma_f32 v[128:129], v[50:51], v[226:227], v[128:129]
	ds_read_b128 v[48:51], v255 offset:672
	v_lshlrev_b32_e32 v224, 16, v38
	v_and_b32_e32 v225, 0xffff0000, v38
	v_lshlrev_b32_e32 v226, 16, v39
	v_and_b32_e32 v227, 0xffff0000, v39
	s_waitcnt lgkmcnt(3)
	v_pk_fma_f32 v[130:131], v[56:57], v[224:225], v[130:131]
	v_pk_fma_f32 v[132:133], v[58:59], v[226:227], v[132:133]
	ds_read_b128 v[56:59], v255 offset:688
	global_load_dwordx4 v[36:39], v248, s[16:17] offset:2048
	s_waitcnt vmcnt(5)
	v_lshlrev_b32_e32 v224, 16, v40
	v_and_b32_e32 v225, 0xffff0000, v40
	v_lshlrev_b32_e32 v226, 16, v41
	v_and_b32_e32 v227, 0xffff0000, v41
	s_waitcnt lgkmcnt(3)
	v_pk_fma_f32 v[126:127], v[60:61], v[224:225], v[126:127]
	v_pk_fma_f32 v[128:129], v[62:63], v[226:227], v[128:129]
	ds_read_b128 v[60:63], v255 offset:2400
	v_lshlrev_b32_e32 v224, 16, v42
	v_and_b32_e32 v225, 0xffff0000, v42
	v_lshlrev_b32_e32 v226, 16, v43
	v_and_b32_e32 v227, 0xffff0000, v43
	s_waitcnt lgkmcnt(3)
	v_pk_fma_f32 v[130:131], v[220:221], v[224:225], v[130:131]
	v_pk_fma_f32 v[132:133], v[222:223], v[226:227], v[132:133]
	ds_read_b128 v[220:223], v255 offset:2416
	global_load_dwordx4 v[40:43], v249, s[16:17] offset:2048
	v_pk_mul_f32 v[224:225], v[126:127], s[18:19] op_sel_hi:[1,0]
	v_pk_mul_f32 v[226:227], v[128:129], s[18:19] op_sel_hi:[1,0]
	v_pk_mul_f32 v[2:3], v[130:131], s[18:19] op_sel_hi:[1,0]
	v_pk_mul_f32 v[134:135], v[132:133], s[18:19] op_sel_hi:[1,0]
	v_exp_f32_e32 v224, v224
	v_exp_f32_e32 v225, v225
	v_exp_f32_e32 v226, v226
	v_exp_f32_e32 v227, v227
	v_exp_f32_e32 v2, v2
	v_exp_f32_e32 v3, v3
	v_exp_f32_e32 v134, v134
	v_exp_f32_e32 v135, v135
	v_pk_add_f32 v[224:225], v[224:225], 1.0 op_sel_hi:[1,0]
	v_pk_add_f32 v[226:227], v[226:227], 1.0 op_sel_hi:[1,0]
	v_pk_add_f32 v[2:3], v[2:3], 1.0 op_sel_hi:[1,0]
	v_pk_add_f32 v[134:135], v[134:135], 1.0 op_sel_hi:[1,0]
	v_rcp_f32_e32 v224, v224
	v_rcp_f32_e32 v225, v225
	v_rcp_f32_e32 v226, v226
	v_rcp_f32_e32 v227, v227
	v_rcp_f32_e32 v2, v2
	v_rcp_f32_e32 v3, v3
	v_rcp_f32_e32 v134, v134
	v_rcp_f32_e32 v135, v135
	v_pk_mul_f32 v[24:25], v[126:127], v[224:225]
	v_pk_mul_f32 v[26:27], v[128:129], v[226:227]
	v_pk_mul_f32 v[64:65], v[130:131], v[2:3]
	v_pk_mul_f32 v[66:67], v[132:133], v[134:135]
	v_pk_mul_f32 v[216:217], v[24:25], v[24:25]
	v_add_f32_e32 v218, v218, v216
	v_add_f32_e32 v218, v217, v218
	v_pk_mul_f32 v[216:217], v[26:27], v[26:27]
	v_add_f32_e32 v218, v218, v216
	v_add_f32_e32 v218, v217, v218
	v_pk_mul_f32 v[216:217], v[64:65], v[64:65]
	v_add_f32_e32 v218, v218, v216
	v_add_f32_e32 v218, v217, v218
	v_pk_mul_f32 v[216:217], v[66:67], v[66:67]
	v_add_f32_e32 v218, v218, v216
	v_add_f32_e32 v218, v217, v218
	s_cmp_lg_u32 s15, 0
	s_cbranch_scc1 .Lpb_sk_7
	s_waitcnt vmcnt(3)
	v_cndmask_b32_e64 v44, 0, v44, s[70:71]
	v_cndmask_b32_e64 v45, 0, v45, s[70:71]
	v_cndmask_b32_e64 v46, 0, v46, s[70:71]
	v_cndmask_b32_e64 v47, 0, v47, s[70:71]
	v_cndmask_b32_e64 v52, 0, v52, s[72:73]
	v_cndmask_b32_e64 v53, 0, v53, s[72:73]
	v_cndmask_b32_e64 v54, 0, v54, s[72:73]
	v_cndmask_b32_e64 v55, 0, v55, s[72:73]
	v_cndmask_b32_e64 v28, 0, v28, s[74:75]
	v_cndmask_b32_e64 v29, 0, v29, s[74:75]
	v_cndmask_b32_e64 v30, 0, v30, s[74:75]
	v_cndmask_b32_e64 v31, 0, v31, s[74:75]
.Lpb_sk_7:
	s_waitcnt vmcnt(5)
	v_lshlrev_b32_e32 v224, 16, v44
	v_and_b32_e32 v225, 0xffff0000, v44
	v_lshlrev_b32_e32 v226, 16, v45
	v_and_b32_e32 v227, 0xffff0000, v45
	s_waitcnt lgkmcnt(3)
	v_pk_fma_f32 v[126:127], v[48:49], v[224:225], 0 op_sel_hi:[1,1,0]
	v_pk_fma_f32 v[128:129], v[50:51], v[226:227], 0 op_sel_hi:[1,1,0]
	ds_read_b128 v[48:51], v255 offset:4128
	v_lshlrev_b32_e32 v224, 16, v46
	v_and_b32_e32 v225, 0xffff0000, v46
	v_lshlrev_b32_e32 v226, 16, v47
	v_and_b32_e32 v227, 0xffff0000, v47
	s_waitcnt lgkmcnt(3)
	v_pk_fma_f32 v[130:131], v[56:57], v[224:225], 0 op_sel_hi:[1,1,0]
	v_pk_fma_f32 v[132:133], v[58:59], v[226:227], 0 op_sel_hi:[1,1,0]
	ds_read_b128 v[56:59], v255 offset:4144
	global_load_dwordx4 v[44:47], v253, s[16:17] offset:2048
	s_waitcnt vmcnt(5)
	v_lshlrev_b32_e32 v224, 16, v52
	v_and_b32_e32 v225, 0xffff0000, v52
	v_lshlrev_b32_e32 v226, 16, v53
	v_and_b32_e32 v227, 0xffff0000, v53
	s_waitcnt lgkmcnt(3)
	v_pk_fma_f32 v[126:127], v[60:61], v[224:225], v[126:127]
	v_pk_fma_f32 v[128:129], v[62:63], v[226:227], v[128:129]
	ds_read_b128 v[60:63], v255 offset:5856
	v_lshlrev_b32_e32 v224, 16, v54
	v_and_b32_e32 v225, 0xffff0000, v54
	v_lshlrev_b32_e32 v226, 16, v55
	v_and_b32_e32 v227, 0xffff0000, v55
	s_waitcnt lgkmcnt(3)
	v_pk_fma_f32 v[130:131], v[220:221], v[224:225], v[130:131]
	v_pk_fma_f32 v[132:133], v[222:223], v[226:227], v[132:133]
	ds_read_b128 v[220:223], v255 offset:5872
	global_load_dwordx4 v[52:55], v254, s[16:17] offset:2048
	s_waitcnt vmcnt(5)
	v_lshlrev_b32_e32 v224, 16, v28
	v_and_b32_e32 v225, 0xffff0000, v28
	v_lshlrev_b32_e32 v226, 16, v29
	v_and_b32_e32 v227, 0xffff0000, v29
	s_waitcnt lgkmcnt(3)
	v_pk_fma_f32 v[126:127], v[48:49], v[224:225], v[126:127]
	v_pk_fma_f32 v[128:129], v[50:51], v[226:227], v[128:129]
	ds_read_b128 v[48:51], v255 offset:1152
	v_lshlrev_b32_e32 v224, 16, v30
	v_and_b32_e32 v225, 0xffff0000, v30
	v_lshlrev_b32_e32 v226, 16, v31
	v_and_b32_e32 v227, 0xffff0000, v31
	s_waitcnt lgkmcnt(3)
	v_pk_fma_f32 v[130:131], v[56:57], v[224:225], v[130:131]
	v_pk_fma_f32 v[132:133], v[58:59], v[226:227], v[132:133]
	ds_read_b128 v[56:59], v255 offset:1168
	global_load_dwordx4 v[28:31], v248, s[16:17] offset:2064
	s_waitcnt vmcnt(5)
	v_lshlrev_b32_e32 v224, 16, v32
	v_and_b32_e32 v225, 0xffff0000, v32
	v_lshlrev_b32_e32 v226, 16, v33
	v_and_b32_e32 v227, 0xffff0000, v33
	s_waitcnt lgkmcnt(3)
	v_pk_fma_f32 v[126:127], v[60:61], v[224:225], v[126:127]
	v_pk_fma_f32 v[128:129], v[62:63], v[226:227], v[128:129]
	ds_read_b128 v[60:63], v255 offset:2880
	v_lshlrev_b32_e32 v224, 16, v34
	v_and_b32_e32 v225, 0xffff0000, v34
	v_lshlrev_b32_e32 v226, 16, v35
	v_and_b32_e32 v227, 0xffff0000, v35
	s_waitcnt lgkmcnt(3)
	v_pk_fma_f32 v[130:131], v[220:221], v[224:225], v[130:131]
	v_pk_fma_f32 v[132:133], v[222:223], v[226:227], v[132:133]
	ds_read_b128 v[220:223], v255 offset:2896
	global_load_dwordx4 v[32:35], v249, s[16:17] offset:2064
	v_pk_mul_f32 v[224:225], v[126:127], s[18:19] op_sel_hi:[1,0]
	v_pk_mul_f32 v[226:227], v[128:129], s[18:19] op_sel_hi:[1,0]
	v_pk_mul_f32 v[2:3], v[130:131], s[18:19] op_sel_hi:[1,0]
	v_pk_mul_f32 v[134:135], v[132:133], s[18:19] op_sel_hi:[1,0]
	v_exp_f32_e32 v224, v224
	v_exp_f32_e32 v225, v225
	v_exp_f32_e32 v226, v226
	v_exp_f32_e32 v227, v227
	v_exp_f32_e32 v2, v2
	v_exp_f32_e32 v3, v3
	v_exp_f32_e32 v134, v134
	v_exp_f32_e32 v135, v135
	v_pk_add_f32 v[224:225], v[224:225], 1.0 op_sel_hi:[1,0]
	v_pk_add_f32 v[226:227], v[226:227], 1.0 op_sel_hi:[1,0]
	v_pk_add_f32 v[2:3], v[2:3], 1.0 op_sel_hi:[1,0]
	v_pk_add_f32 v[134:135], v[134:135], 1.0 op_sel_hi:[1,0]
	v_rcp_f32_e32 v224, v224
	v_rcp_f32_e32 v225, v225
	v_rcp_f32_e32 v226, v226
	v_rcp_f32_e32 v227, v227
	v_rcp_f32_e32 v2, v2
	v_rcp_f32_e32 v3, v3
	v_rcp_f32_e32 v134, v134
	v_rcp_f32_e32 v135, v135
	v_pk_mul_f32 v[68:69], v[126:127], v[224:225]
	v_pk_mul_f32 v[70:71], v[128:129], v[226:227]
	v_pk_mul_f32 v[122:123], v[130:131], v[2:3]
	v_pk_mul_f32 v[124:125], v[132:133], v[134:135]
	v_pk_mul_f32 v[216:217], v[68:69], v[68:69]
	v_add_f32_e32 v218, v218, v216
	v_add_f32_e32 v218, v217, v218
	v_pk_mul_f32 v[216:217], v[70:71], v[70:71]
	v_add_f32_e32 v218, v218, v216
	v_add_f32_e32 v218, v217, v218
	v_pk_mul_f32 v[216:217], v[122:123], v[122:123]
	v_add_f32_e32 v218, v218, v216
	v_add_f32_e32 v218, v217, v218
	v_pk_mul_f32 v[216:217], v[124:125], v[124:125]
	v_add_f32_e32 v218, v218, v216
	v_add_f32_e32 v218, v217, v218
	s_nop 1
	v_add_f32_dpp v119, v218, v218 quad_perm:[1,0,3,2] row_mask:0xf bank_mask:0xf
	s_nop 1
	v_add_f32_dpp v216, v119, v119 quad_perm:[2,3,0,1] row_mask:0xf bank_mask:0xf
	v_add_f32_e32 v216, 0x358637bd, v216
	v_mul_f32_e32 v119, 0x4b800000, v216
	v_cmp_gt_f32_e32 vcc, 0x800000, v216
	s_nop 1
	v_cndmask_b32_e32 v216, v216, v119, vcc
	v_rsq_f32_e32 v216, v216
	s_nop 0
	v_mul_f32_e32 v119, 0x45800000, v216
	v_cndmask_b32_e32 v216, v216, v119, vcc
	v_pk_mul_f32 v[8:9], v[8:9], v[216:217] op_sel_hi:[1,0]
	v_pk_mul_f32 v[10:11], v[10:11], v[216:217] op_sel_hi:[1,0]
	v_pk_mul_f32 v[12:13], v[12:13], v[216:217] op_sel_hi:[1,0]
	v_pk_mul_f32 v[14:15], v[14:15], v[216:217] op_sel_hi:[1,0]
	v_pk_mul_f32 v[16:17], v[16:17], v[216:217] op_sel_hi:[1,0]
	v_pk_mul_f32 v[18:19], v[18:19], v[216:217] op_sel_hi:[1,0]
	v_pk_mul_f32 v[20:21], v[20:21], v[216:217] op_sel_hi:[1,0]
	v_pk_mul_f32 v[22:23], v[22:23], v[216:217] op_sel_hi:[1,0]
	v_pk_mul_f32 v[24:25], v[24:25], v[216:217] op_sel_hi:[1,0]
	v_pk_mul_f32 v[26:27], v[26:27], v[216:217] op_sel_hi:[1,0]
	v_pk_mul_f32 v[64:65], v[64:65], v[216:217] op_sel_hi:[1,0]
	v_pk_mul_f32 v[66:67], v[66:67], v[216:217] op_sel_hi:[1,0]
	v_pk_mul_f32 v[68:69], v[68:69], v[216:217] op_sel_hi:[1,0]
	v_pk_mul_f32 v[70:71], v[70:71], v[216:217] op_sel_hi:[1,0]
	v_pk_mul_f32 v[122:123], v[122:123], v[216:217] op_sel_hi:[1,0]
	v_pk_mul_f32 v[124:125], v[124:125], v[216:217] op_sel_hi:[1,0]
	v_mov_b32_e32 v218, 0
	v_cvt_pk_bf16_f32 v224, v8, v9
	v_cvt_pk_bf16_f32 v225, v10, v11
	v_cvt_pk_bf16_f32 v226, v12, v13
	v_cvt_pk_bf16_f32 v227, v14, v15
	v_xor_b32_e32 v119, 0, v113
	v_lshl_add_u32 v119, v119, 4, v111
	ds_write_b128 v119, v[224:227]
	v_pk_mul_f32 v[2:3], v[230:231], v[8:9] op_sel:[1,0] op_sel_hi:[1,1]
	v_cvt_pk_bf16_f32 v119, v2, v3
	global_store_short v115, v119, s[92:93] offset:0
	global_store_short_d16_hi v115, v119, s[92:93] offset:128
	v_pk_mul_f32 v[134:135], v[230:231], v[10:11] op_sel:[1,0] op_sel_hi:[1,1]
	v_cvt_pk_bf16_f32 v121, v134, v135
	global_store_short v115, v121, s[92:93] offset:256
	global_store_short_d16_hi v115, v121, s[92:93] offset:384
	v_pk_mul_f32 v[2:3], v[230:231], v[12:13] op_sel:[1,0] op_sel_hi:[1,1]
	v_cvt_pk_bf16_f32 v119, v2, v3
	global_store_short v115, v119, s[92:93] offset:512
	global_store_short_d16_hi v115, v119, s[92:93] offset:640
	v_pk_mul_f32 v[134:135], v[230:231], v[14:15] op_sel:[1,0] op_sel_hi:[1,1]
	v_cvt_pk_bf16_f32 v121, v134, v135
	global_store_short v115, v121, s[92:93] offset:768
	global_store_short_d16_hi v115, v121, s[92:93] offset:896
	v_cvt_pk_bf16_f32 v224, v16, v17
	v_cvt_pk_bf16_f32 v225, v18, v19
	v_cvt_pk_bf16_f32 v226, v20, v21
	v_cvt_pk_bf16_f32 v227, v22, v23
	v_xor_b32_e32 v119, 1, v113
	v_lshl_add_u32 v119, v119, 4, v111
	ds_write_b128 v119, v[224:227]
	v_pk_mul_f32 v[2:3], v[230:231], v[16:17] op_sel:[1,0] op_sel_hi:[1,1]
	v_cvt_pk_bf16_f32 v119, v2, v3
	global_store_short v115, v119, s[92:93] offset:1024
	global_store_short_d16_hi v115, v119, s[92:93] offset:1152
	v_pk_mul_f32 v[134:135], v[230:231], v[18:19] op_sel:[1,0] op_sel_hi:[1,1]
	v_cvt_pk_bf16_f32 v121, v134, v135
	global_store_short v115, v121, s[92:93] offset:1280
	global_store_short_d16_hi v115, v121, s[92:93] offset:1408
	v_pk_mul_f32 v[2:3], v[230:231], v[20:21] op_sel:[1,0] op_sel_hi:[1,1]
	v_cvt_pk_bf16_f32 v119, v2, v3
	global_store_short v115, v119, s[92:93] offset:1536
	global_store_short_d16_hi v115, v119, s[92:93] offset:1664
	v_pk_mul_f32 v[134:135], v[230:231], v[22:23] op_sel:[1,0] op_sel_hi:[1,1]
	v_cvt_pk_bf16_f32 v121, v134, v135
	global_store_short v115, v121, s[92:93] offset:1792
	global_store_short_d16_hi v115, v121, s[92:93] offset:1920
	v_cvt_pk_bf16_f32 v224, v24, v25
	v_cvt_pk_bf16_f32 v225, v26, v27
	v_cvt_pk_bf16_f32 v226, v64, v65
	v_cvt_pk_bf16_f32 v227, v66, v67
	v_xor_b32_e32 v119, 2, v113
	v_lshl_add_u32 v119, v119, 4, v111
	ds_write_b128 v119, v[224:227]
	v_pk_mul_f32 v[2:3], v[230:231], v[24:25] op_sel:[1,0] op_sel_hi:[1,1]
	v_cvt_pk_bf16_f32 v119, v2, v3
	global_store_short v115, v119, s[92:93] offset:2048
	global_store_short_d16_hi v115, v119, s[92:93] offset:2176
	v_pk_mul_f32 v[134:135], v[230:231], v[26:27] op_sel:[1,0] op_sel_hi:[1,1]
	v_cvt_pk_bf16_f32 v121, v134, v135
	global_store_short v115, v121, s[92:93] offset:2304
	global_store_short_d16_hi v115, v121, s[92:93] offset:2432
	v_pk_mul_f32 v[2:3], v[230:231], v[64:65] op_sel:[1,0] op_sel_hi:[1,1]
	v_cvt_pk_bf16_f32 v119, v2, v3
	global_store_short v115, v119, s[92:93] offset:2560
	global_store_short_d16_hi v115, v119, s[92:93] offset:2688
	v_pk_mul_f32 v[134:135], v[230:231], v[66:67] op_sel:[1,0] op_sel_hi:[1,1]
	v_cvt_pk_bf16_f32 v121, v134, v135
	global_store_short v115, v121, s[92:93] offset:2816
	global_store_short_d16_hi v115, v121, s[92:93] offset:2944
	v_cvt_pk_bf16_f32 v224, v68, v69
	v_cvt_pk_bf16_f32 v225, v70, v71
	v_cvt_pk_bf16_f32 v226, v122, v123
	v_cvt_pk_bf16_f32 v227, v124, v125
	v_xor_b32_e32 v119, 3, v113
	v_lshl_add_u32 v119, v119, 4, v111
	ds_write_b128 v119, v[224:227]
	v_pk_mul_f32 v[2:3], v[230:231], v[68:69] op_sel:[1,0] op_sel_hi:[1,1]
	v_cvt_pk_bf16_f32 v119, v2, v3
	global_store_short v115, v119, s[92:93] offset:3072
	global_store_short_d16_hi v115, v119, s[92:93] offset:3200
	v_pk_mul_f32 v[134:135], v[230:231], v[70:71] op_sel:[1,0] op_sel_hi:[1,1]
	v_cvt_pk_bf16_f32 v121, v134, v135
	global_store_short v115, v121, s[92:93] offset:3328
	global_store_short_d16_hi v115, v121, s[92:93] offset:3456
	v_pk_mul_f32 v[2:3], v[230:231], v[122:123] op_sel:[1,0] op_sel_hi:[1,1]
	v_cvt_pk_bf16_f32 v119, v2, v3
	global_store_short v115, v119, s[92:93] offset:3584
	global_store_short_d16_hi v115, v119, s[92:93] offset:3712
	v_pk_mul_f32 v[134:135], v[230:231], v[124:125] op_sel:[1,0] op_sel_hi:[1,1]
	v_cvt_pk_bf16_f32 v121, v134, v135
	global_store_short v115, v121, s[92:93] offset:3840
	global_store_short_d16_hi v115, v121, s[92:93] offset:3968
	s_cmp_lg_u32 s15, 0
	s_cbranch_scc1 .Lpb_sk_8
	s_waitcnt vmcnt(35)
	v_cndmask_b32_e64 v36, 0, v36, s[70:71]
	v_cndmask_b32_e64 v37, 0, v37, s[70:71]
	v_cndmask_b32_e64 v38, 0, v38, s[70:71]
	v_cndmask_b32_e64 v39, 0, v39, s[70:71]
	v_cndmask_b32_e64 v40, 0, v40, s[72:73]
	v_cndmask_b32_e64 v41, 0, v41, s[72:73]
	v_cndmask_b32_e64 v42, 0, v42, s[72:73]
	v_cndmask_b32_e64 v43, 0, v43, s[72:73]
	v_cndmask_b32_e64 v44, 0, v44, s[74:75]
	v_cndmask_b32_e64 v45, 0, v45, s[74:75]
	v_cndmask_b32_e64 v46, 0, v46, s[74:75]
	v_cndmask_b32_e64 v47, 0, v47, s[74:75]
.Lpb_sk_8:
	s_waitcnt vmcnt(37)
	v_lshlrev_b32_e32 v224, 16, v36
	v_and_b32_e32 v225, 0xffff0000, v36
	v_lshlrev_b32_e32 v226, 16, v37
	v_and_b32_e32 v227, 0xffff0000, v37
	s_waitcnt lgkmcnt(7)
	v_pk_fma_f32 v[126:127], v[48:49], v[224:225], 0 op_sel_hi:[1,1,0]
	v_pk_fma_f32 v[128:129], v[50:51], v[226:227], 0 op_sel_hi:[1,1,0]
	ds_read_b128 v[48:51], v255 offset:4608
	v_lshlrev_b32_e32 v224, 16, v38
	v_and_b32_e32 v225, 0xffff0000, v38
	v_lshlrev_b32_e32 v226, 16, v39
	v_and_b32_e32 v227, 0xffff0000, v39
	s_waitcnt lgkmcnt(7)
	v_pk_fma_f32 v[130:131], v[56:57], v[224:225], 0 op_sel_hi:[1,1,0]
	v_pk_fma_f32 v[132:133], v[58:59], v[226:227], 0 op_sel_hi:[1,1,0]
	ds_read_b128 v[56:59], v255 offset:4624
	global_load_dwordx4 v[36:39], v253, s[16:17] offset:2064
	s_waitcnt vmcnt(37)
	v_lshlrev_b32_e32 v224, 16, v40
	v_and_b32_e32 v225, 0xffff0000, v40
	v_lshlrev_b32_e32 v226, 16, v41
	v_and_b32_e32 v227, 0xffff0000, v41
	s_waitcnt lgkmcnt(7)
	v_pk_fma_f32 v[126:127], v[60:61], v[224:225], v[126:127]
	v_pk_fma_f32 v[128:129], v[62:63], v[226:227], v[128:129]
	ds_read_b128 v[60:63], v255 offset:6336
	v_lshlrev_b32_e32 v224, 16, v42
	v_and_b32_e32 v225, 0xffff0000, v42
	v_lshlrev_b32_e32 v226, 16, v43
	v_and_b32_e32 v227, 0xffff0000, v43
	s_waitcnt lgkmcnt(7)
	v_pk_fma_f32 v[130:131], v[220:221], v[224:225], v[130:131]
	v_pk_fma_f32 v[132:133], v[222:223], v[226:227], v[132:133]
	ds_read_b128 v[220:223], v255 offset:6352
	global_load_dwordx4 v[40:43], v254, s[16:17] offset:2064
	s_waitcnt vmcnt(37)
	v_lshlrev_b32_e32 v224, 16, v44
	v_and_b32_e32 v225, 0xffff0000, v44
	v_lshlrev_b32_e32 v226, 16, v45
	v_and_b32_e32 v227, 0xffff0000, v45
	s_waitcnt lgkmcnt(3)
	v_pk_fma_f32 v[126:127], v[48:49], v[224:225], v[126:127]
	v_pk_fma_f32 v[128:129], v[50:51], v[226:227], v[128:129]
	ds_read_b128 v[48:51], v255 offset:1184
	v_lshlrev_b32_e32 v224, 16, v46
	v_and_b32_e32 v225, 0xffff0000, v46
	v_lshlrev_b32_e32 v226, 16, v47
	v_and_b32_e32 v227, 0xffff0000, v47
	s_waitcnt lgkmcnt(3)
	v_pk_fma_f32 v[130:131], v[56:57], v[224:225], v[130:131]
	v_pk_fma_f32 v[132:133], v[58:59], v[226:227], v[132:133]
	ds_read_b128 v[56:59], v255 offset:1200
	global_load_dwordx4 v[44:47], v248, s[16:17] offset:2080
	s_waitcnt vmcnt(37)
	v_lshlrev_b32_e32 v224, 16, v52
	v_and_b32_e32 v225, 0xffff0000, v52
	v_lshlrev_b32_e32 v226, 16, v53
	v_and_b32_e32 v227, 0xffff0000, v53
	s_waitcnt lgkmcnt(3)
	v_pk_fma_f32 v[126:127], v[60:61], v[224:225], v[126:127]
	v_pk_fma_f32 v[128:129], v[62:63], v[226:227], v[128:129]
	ds_read_b128 v[60:63], v255 offset:2912
	v_lshlrev_b32_e32 v224, 16, v54
	v_and_b32_e32 v225, 0xffff0000, v54
	v_lshlrev_b32_e32 v226, 16, v55
	v_and_b32_e32 v227, 0xffff0000, v55
	s_waitcnt lgkmcnt(3)
	v_pk_fma_f32 v[130:131], v[220:221], v[224:225], v[130:131]
	v_pk_fma_f32 v[132:133], v[222:223], v[226:227], v[132:133]
	ds_read_b128 v[220:223], v255 offset:2928
	global_load_dwordx4 v[52:55], v249, s[16:17] offset:2080
	v_pk_mul_f32 v[224:225], v[126:127], s[18:19] op_sel_hi:[1,0]
	v_pk_mul_f32 v[226:227], v[128:129], s[18:19] op_sel_hi:[1,0]
	v_pk_mul_f32 v[2:3], v[130:131], s[18:19] op_sel_hi:[1,0]
	v_pk_mul_f32 v[134:135], v[132:133], s[18:19] op_sel_hi:[1,0]
	v_exp_f32_e32 v224, v224
	v_exp_f32_e32 v225, v225
	v_exp_f32_e32 v226, v226
	v_exp_f32_e32 v227, v227
	v_exp_f32_e32 v2, v2
	v_exp_f32_e32 v3, v3
	v_exp_f32_e32 v134, v134
	v_exp_f32_e32 v135, v135
	v_pk_add_f32 v[224:225], v[224:225], 1.0 op_sel_hi:[1,0]
	v_pk_add_f32 v[226:227], v[226:227], 1.0 op_sel_hi:[1,0]
	v_pk_add_f32 v[2:3], v[2:3], 1.0 op_sel_hi:[1,0]
	v_pk_add_f32 v[134:135], v[134:135], 1.0 op_sel_hi:[1,0]
	v_rcp_f32_e32 v224, v224
	v_rcp_f32_e32 v225, v225
	v_rcp_f32_e32 v226, v226
	v_rcp_f32_e32 v227, v227
	v_rcp_f32_e32 v2, v2
	v_rcp_f32_e32 v3, v3
	v_rcp_f32_e32 v134, v134
	v_rcp_f32_e32 v135, v135
	v_pk_mul_f32 v[8:9], v[126:127], v[224:225]
	v_pk_mul_f32 v[10:11], v[128:129], v[226:227]
	v_pk_mul_f32 v[12:13], v[130:131], v[2:3]
	v_pk_mul_f32 v[14:15], v[132:133], v[134:135]
	s_cmp_lg_u32 s15, 0
	s_cbranch_scc1 .Lpb_sk_9
	s_waitcnt vmcnt(3)
	v_cndmask_b32_e64 v28, 0, v28, s[70:71]
	v_cndmask_b32_e64 v29, 0, v29, s[70:71]
	v_cndmask_b32_e64 v30, 0, v30, s[70:71]
	v_cndmask_b32_e64 v31, 0, v31, s[70:71]
	v_cndmask_b32_e64 v32, 0, v32, s[72:73]
	v_cndmask_b32_e64 v33, 0, v33, s[72:73]
	v_cndmask_b32_e64 v34, 0, v34, s[72:73]
	v_cndmask_b32_e64 v35, 0, v35, s[72:73]
	v_cndmask_b32_e64 v36, 0, v36, s[74:75]
	v_cndmask_b32_e64 v37, 0, v37, s[74:75]
	v_cndmask_b32_e64 v38, 0, v38, s[74:75]
	v_cndmask_b32_e64 v39, 0, v39, s[74:75]
.Lpb_sk_9:
	s_waitcnt vmcnt(37)
	v_lshlrev_b32_e32 v224, 16, v28
	v_and_b32_e32 v225, 0xffff0000, v28
	v_lshlrev_b32_e32 v226, 16, v29
	v_and_b32_e32 v227, 0xffff0000, v29
	s_waitcnt lgkmcnt(3)
	v_pk_fma_f32 v[126:127], v[48:49], v[224:225], 0 op_sel_hi:[1,1,0]
	v_pk_fma_f32 v[128:129], v[50:51], v[226:227], 0 op_sel_hi:[1,1,0]
	ds_read_b128 v[48:51], v255 offset:4640
	v_lshlrev_b32_e32 v224, 16, v30
	v_and_b32_e32 v225, 0xffff0000, v30
	v_lshlrev_b32_e32 v226, 16, v31
	v_and_b32_e32 v227, 0xffff0000, v31
	s_waitcnt lgkmcnt(3)
	v_pk_fma_f32 v[130:131], v[56:57], v[224:225], 0 op_sel_hi:[1,1,0]
	v_pk_fma_f32 v[132:133], v[58:59], v[226:227], 0 op_sel_hi:[1,1,0]
	ds_read_b128 v[56:59], v255 offset:4656
	global_load_dwordx4 v[28:31], v253, s[16:17] offset:2080
	s_waitcnt vmcnt(37)
	v_lshlrev_b32_e32 v224, 16, v32
	v_and_b32_e32 v225, 0xffff0000, v32
	v_lshlrev_b32_e32 v226, 16, v33
	v_and_b32_e32 v227, 0xffff0000, v33
	s_waitcnt lgkmcnt(3)
	v_pk_fma_f32 v[126:127], v[60:61], v[224:225], v[126:127]
	v_pk_fma_f32 v[128:129], v[62:63], v[226:227], v[128:129]
	ds_read_b128 v[60:63], v255 offset:6368
	v_lshlrev_b32_e32 v224, 16, v34
	v_and_b32_e32 v225, 0xffff0000, v34
	v_lshlrev_b32_e32 v226, 16, v35
	v_and_b32_e32 v227, 0xffff0000, v35
	s_waitcnt lgkmcnt(3)
	v_pk_fma_f32 v[130:131], v[220:221], v[224:225], v[130:131]
	v_pk_fma_f32 v[132:133], v[222:223], v[226:227], v[132:133]
	ds_read_b128 v[220:223], v255 offset:6384
	global_load_dwordx4 v[32:35], v254, s[16:17] offset:2080
	s_waitcnt vmcnt(5)
	v_lshlrev_b32_e32 v224, 16, v36
	v_and_b32_e32 v225, 0xffff0000, v36
	v_lshlrev_b32_e32 v226, 16, v37
	v_and_b32_e32 v227, 0xffff0000, v37
	s_waitcnt lgkmcnt(3)
	v_pk_fma_f32 v[126:127], v[48:49], v[224:225], v[126:127]
	v_pk_fma_f32 v[128:129], v[50:51], v[226:227], v[128:129]
	ds_read_b128 v[48:51], v255 offset:1216
	v_lshlrev_b32_e32 v224, 16, v38
	v_and_b32_e32 v225, 0xffff0000, v38
	v_lshlrev_b32_e32 v226, 16, v39
	v_and_b32_e32 v227, 0xffff0000, v39
	s_waitcnt lgkmcnt(3)
	v_pk_fma_f32 v[130:131], v[56:57], v[224:225], v[130:131]
	v_pk_fma_f32 v[132:133], v[58:59], v[226:227], v[132:133]
	ds_read_b128 v[56:59], v255 offset:1232
	global_load_dwordx4 v[36:39], v248, s[16:17] offset:2096
	s_waitcnt vmcnt(5)
	v_lshlrev_b32_e32 v224, 16, v40
	v_and_b32_e32 v225, 0xffff0000, v40
	v_lshlrev_b32_e32 v226, 16, v41
	v_and_b32_e32 v227, 0xffff0000, v41
	s_waitcnt lgkmcnt(3)
	v_pk_fma_f32 v[126:127], v[60:61], v[224:225], v[126:127]
	v_pk_fma_f32 v[128:129], v[62:63], v[226:227], v[128:129]
	ds_read_b128 v[60:63], v255 offset:2944
	v_lshlrev_b32_e32 v224, 16, v42
	v_and_b32_e32 v225, 0xffff0000, v42
	v_lshlrev_b32_e32 v226, 16, v43
	v_and_b32_e32 v227, 0xffff0000, v43
	s_waitcnt lgkmcnt(3)
	v_pk_fma_f32 v[130:131], v[220:221], v[224:225], v[130:131]
	v_pk_fma_f32 v[132:133], v[222:223], v[226:227], v[132:133]
	ds_read_b128 v[220:223], v255 offset:2960
	global_load_dwordx4 v[40:43], v249, s[16:17] offset:2096
	v_pk_mul_f32 v[224:225], v[126:127], s[18:19] op_sel_hi:[1,0]
	v_pk_mul_f32 v[226:227], v[128:129], s[18:19] op_sel_hi:[1,0]
	v_pk_mul_f32 v[2:3], v[130:131], s[18:19] op_sel_hi:[1,0]
	v_pk_mul_f32 v[134:135], v[132:133], s[18:19] op_sel_hi:[1,0]
	v_exp_f32_e32 v224, v224
	v_exp_f32_e32 v225, v225
	v_exp_f32_e32 v226, v226
	v_exp_f32_e32 v227, v227
	v_exp_f32_e32 v2, v2
	v_exp_f32_e32 v3, v3
	v_exp_f32_e32 v134, v134
	v_exp_f32_e32 v135, v135
	v_pk_add_f32 v[224:225], v[224:225], 1.0 op_sel_hi:[1,0]
	v_pk_add_f32 v[226:227], v[226:227], 1.0 op_sel_hi:[1,0]
	v_pk_add_f32 v[2:3], v[2:3], 1.0 op_sel_hi:[1,0]
	v_pk_add_f32 v[134:135], v[134:135], 1.0 op_sel_hi:[1,0]
	v_rcp_f32_e32 v224, v224
	v_rcp_f32_e32 v225, v225
	v_rcp_f32_e32 v226, v226
	v_rcp_f32_e32 v227, v227
	v_rcp_f32_e32 v2, v2
	v_rcp_f32_e32 v3, v3
	v_rcp_f32_e32 v134, v134
	v_rcp_f32_e32 v135, v135
	v_pk_mul_f32 v[16:17], v[126:127], v[224:225]
	v_pk_mul_f32 v[18:19], v[128:129], v[226:227]
	v_pk_mul_f32 v[20:21], v[130:131], v[2:3]
	v_pk_mul_f32 v[22:23], v[132:133], v[134:135]
	s_cmp_lg_u32 s15, 0
	s_cbranch_scc1 .Lpb_sk_10
	s_waitcnt vmcnt(3)
	v_cndmask_b32_e64 v44, 0, v44, s[70:71]
	v_cndmask_b32_e64 v45, 0, v45, s[70:71]
	v_cndmask_b32_e64 v46, 0, v46, s[70:71]
	v_cndmask_b32_e64 v47, 0, v47, s[70:71]
	v_cndmask_b32_e64 v52, 0, v52, s[72:73]
	v_cndmask_b32_e64 v53, 0, v53, s[72:73]
	v_cndmask_b32_e64 v54, 0, v54, s[72:73]
	v_cndmask_b32_e64 v55, 0, v55, s[72:73]
	v_cndmask_b32_e64 v28, 0, v28, s[74:75]
	v_cndmask_b32_e64 v29, 0, v29, s[74:75]
	v_cndmask_b32_e64 v30, 0, v30, s[74:75]
	v_cndmask_b32_e64 v31, 0, v31, s[74:75]
.Lpb_sk_10:
	s_waitcnt vmcnt(5)
	v_lshlrev_b32_e32 v224, 16, v44
	v_and_b32_e32 v225, 0xffff0000, v44
	v_lshlrev_b32_e32 v226, 16, v45
	v_and_b32_e32 v227, 0xffff0000, v45
	s_waitcnt lgkmcnt(3)
	v_pk_fma_f32 v[126:127], v[48:49], v[224:225], 0 op_sel_hi:[1,1,0]
	v_pk_fma_f32 v[128:129], v[50:51], v[226:227], 0 op_sel_hi:[1,1,0]
	ds_read_b128 v[48:51], v255 offset:4672
	v_lshlrev_b32_e32 v224, 16, v46
	v_and_b32_e32 v225, 0xffff0000, v46
	v_lshlrev_b32_e32 v226, 16, v47
	v_and_b32_e32 v227, 0xffff0000, v47
	s_waitcnt lgkmcnt(3)
	v_pk_fma_f32 v[130:131], v[56:57], v[224:225], 0 op_sel_hi:[1,1,0]
	v_pk_fma_f32 v[132:133], v[58:59], v[226:227], 0 op_sel_hi:[1,1,0]
	ds_read_b128 v[56:59], v255 offset:4688
	global_load_dwordx4 v[44:47], v253, s[16:17] offset:2096
	s_waitcnt vmcnt(5)
	v_lshlrev_b32_e32 v224, 16, v52
	v_and_b32_e32 v225, 0xffff0000, v52
	v_lshlrev_b32_e32 v226, 16, v53
	v_and_b32_e32 v227, 0xffff0000, v53
	s_waitcnt lgkmcnt(3)
	v_pk_fma_f32 v[126:127], v[60:61], v[224:225], v[126:127]
	v_pk_fma_f32 v[128:129], v[62:63], v[226:227], v[128:129]
	ds_read_b128 v[60:63], v255 offset:6400
	v_lshlrev_b32_e32 v224, 16, v54
	v_and_b32_e32 v225, 0xffff0000, v54
	v_lshlrev_b32_e32 v226, 16, v55
	v_and_b32_e32 v227, 0xffff0000, v55
	s_waitcnt lgkmcnt(3)
	v_pk_fma_f32 v[130:131], v[220:221], v[224:225], v[130:131]
	v_pk_fma_f32 v[132:133], v[222:223], v[226:227], v[132:133]
	ds_read_b128 v[220:223], v255 offset:6416
	global_load_dwordx4 v[52:55], v254, s[16:17] offset:2096
	s_waitcnt vmcnt(5)
	v_lshlrev_b32_e32 v224, 16, v28
	v_and_b32_e32 v225, 0xffff0000, v28
	v_lshlrev_b32_e32 v226, 16, v29
	v_and_b32_e32 v227, 0xffff0000, v29
	s_waitcnt lgkmcnt(3)
	v_pk_fma_f32 v[126:127], v[48:49], v[224:225], v[126:127]
	v_pk_fma_f32 v[128:129], v[50:51], v[226:227], v[128:129]
	ds_read_b128 v[48:51], v255 offset:1248
	v_lshlrev_b32_e32 v224, 16, v30
	v_and_b32_e32 v225, 0xffff0000, v30
	v_lshlrev_b32_e32 v226, 16, v31
	v_and_b32_e32 v227, 0xffff0000, v31
	s_waitcnt lgkmcnt(3)
	v_pk_fma_f32 v[130:131], v[56:57], v[224:225], v[130:131]
	v_pk_fma_f32 v[132:133], v[58:59], v[226:227], v[132:133]
	ds_read_b128 v[56:59], v255 offset:1264
	s_waitcnt vmcnt(4)
	v_lshlrev_b32_e32 v224, 16, v32
	v_and_b32_e32 v225, 0xffff0000, v32
	v_lshlrev_b32_e32 v226, 16, v33
	v_and_b32_e32 v227, 0xffff0000, v33
	s_waitcnt lgkmcnt(3)
	v_pk_fma_f32 v[126:127], v[60:61], v[224:225], v[126:127]
	v_pk_fma_f32 v[128:129], v[62:63], v[226:227], v[128:129]
	ds_read_b128 v[60:63], v255 offset:2976
	v_lshlrev_b32_e32 v224, 16, v34
	v_and_b32_e32 v225, 0xffff0000, v34
	v_lshlrev_b32_e32 v226, 16, v35
	v_and_b32_e32 v227, 0xffff0000, v35
	s_waitcnt lgkmcnt(3)
	v_pk_fma_f32 v[130:131], v[220:221], v[224:225], v[130:131]
	v_pk_fma_f32 v[132:133], v[222:223], v[226:227], v[132:133]
	ds_read_b128 v[220:223], v255 offset:2992
	v_pk_mul_f32 v[224:225], v[126:127], s[18:19] op_sel_hi:[1,0]
	v_pk_mul_f32 v[226:227], v[128:129], s[18:19] op_sel_hi:[1,0]
	v_pk_mul_f32 v[2:3], v[130:131], s[18:19] op_sel_hi:[1,0]
	v_pk_mul_f32 v[134:135], v[132:133], s[18:19] op_sel_hi:[1,0]
	v_exp_f32_e32 v224, v224
	v_exp_f32_e32 v225, v225
	v_exp_f32_e32 v226, v226
	v_exp_f32_e32 v227, v227
	v_exp_f32_e32 v2, v2
	v_exp_f32_e32 v3, v3
	v_exp_f32_e32 v134, v134
	v_exp_f32_e32 v135, v135
	v_pk_add_f32 v[224:225], v[224:225], 1.0 op_sel_hi:[1,0]
	v_pk_add_f32 v[226:227], v[226:227], 1.0 op_sel_hi:[1,0]
	v_pk_add_f32 v[2:3], v[2:3], 1.0 op_sel_hi:[1,0]
	v_pk_add_f32 v[134:135], v[134:135], 1.0 op_sel_hi:[1,0]
	v_rcp_f32_e32 v224, v224
	v_rcp_f32_e32 v225, v225
	v_rcp_f32_e32 v226, v226
	v_rcp_f32_e32 v227, v227
	v_rcp_f32_e32 v2, v2
	v_rcp_f32_e32 v3, v3
	v_rcp_f32_e32 v134, v134
	v_rcp_f32_e32 v135, v135
	v_pk_mul_f32 v[24:25], v[126:127], v[224:225]
	v_pk_mul_f32 v[26:27], v[128:129], v[226:227]
	v_pk_mul_f32 v[64:65], v[130:131], v[2:3]
	v_pk_mul_f32 v[66:67], v[132:133], v[134:135]
	s_cmp_lg_u32 s15, 0
	s_cbranch_scc1 .Lpb_sk_11
	s_waitcnt vmcnt(1)
	v_cndmask_b32_e64 v36, 0, v36, s[70:71]
	v_cndmask_b32_e64 v37, 0, v37, s[70:71]
	v_cndmask_b32_e64 v38, 0, v38, s[70:71]
	v_cndmask_b32_e64 v39, 0, v39, s[70:71]
	v_cndmask_b32_e64 v40, 0, v40, s[72:73]
	v_cndmask_b32_e64 v41, 0, v41, s[72:73]
	v_cndmask_b32_e64 v42, 0, v42, s[72:73]
	v_cndmask_b32_e64 v43, 0, v43, s[72:73]
	v_cndmask_b32_e64 v44, 0, v44, s[74:75]
	v_cndmask_b32_e64 v45, 0, v45, s[74:75]
	v_cndmask_b32_e64 v46, 0, v46, s[74:75]
	v_cndmask_b32_e64 v47, 0, v47, s[74:75]
.Lpb_sk_11:
	s_waitcnt vmcnt(3)
	v_lshlrev_b32_e32 v224, 16, v36
	v_and_b32_e32 v225, 0xffff0000, v36
	v_lshlrev_b32_e32 v226, 16, v37
	v_and_b32_e32 v227, 0xffff0000, v37
	s_waitcnt lgkmcnt(3)
	v_pk_fma_f32 v[126:127], v[48:49], v[224:225], 0 op_sel_hi:[1,1,0]
	v_pk_fma_f32 v[128:129], v[50:51], v[226:227], 0 op_sel_hi:[1,1,0]
	ds_read_b128 v[48:51], v255 offset:4704
	v_lshlrev_b32_e32 v224, 16, v38
	v_and_b32_e32 v225, 0xffff0000, v38
	v_lshlrev_b32_e32 v226, 16, v39
	v_and_b32_e32 v227, 0xffff0000, v39
	s_waitcnt lgkmcnt(3)
	v_pk_fma_f32 v[130:131], v[56:57], v[224:225], 0 op_sel_hi:[1,1,0]
	v_pk_fma_f32 v[132:133], v[58:59], v[226:227], 0 op_sel_hi:[1,1,0]
	ds_read_b128 v[56:59], v255 offset:4720
	s_waitcnt vmcnt(2)
	v_lshlrev_b32_e32 v224, 16, v40
	v_and_b32_e32 v225, 0xffff0000, v40
	v_lshlrev_b32_e32 v226, 16, v41
	v_and_b32_e32 v227, 0xffff0000, v41
	s_waitcnt lgkmcnt(3)
	v_pk_fma_f32 v[126:127], v[60:61], v[224:225], v[126:127]
	v_pk_fma_f32 v[128:129], v[62:63], v[226:227], v[128:129]
	ds_read_b128 v[60:63], v255 offset:6432
	v_lshlrev_b32_e32 v224, 16, v42
	v_and_b32_e32 v225, 0xffff0000, v42
	v_lshlrev_b32_e32 v226, 16, v43
	v_and_b32_e32 v227, 0xffff0000, v43
	s_waitcnt lgkmcnt(3)
	v_pk_fma_f32 v[130:131], v[220:221], v[224:225], v[130:131]
	v_pk_fma_f32 v[132:133], v[222:223], v[226:227], v[132:133]
	ds_read_b128 v[220:223], v255 offset:6448
	s_waitcnt vmcnt(1)
	v_lshlrev_b32_e32 v224, 16, v44
	v_and_b32_e32 v225, 0xffff0000, v44
	v_lshlrev_b32_e32 v226, 16, v45
	v_and_b32_e32 v227, 0xffff0000, v45
	s_waitcnt lgkmcnt(3)
	v_pk_fma_f32 v[126:127], v[48:49], v[224:225], v[126:127]
	v_pk_fma_f32 v[128:129], v[50:51], v[226:227], v[128:129]
	v_lshlrev_b32_e32 v224, 16, v46
	v_and_b32_e32 v225, 0xffff0000, v46
	v_lshlrev_b32_e32 v226, 16, v47
	v_and_b32_e32 v227, 0xffff0000, v47
	s_waitcnt lgkmcnt(2)
	v_pk_fma_f32 v[130:131], v[56:57], v[224:225], v[130:131]
	v_pk_fma_f32 v[132:133], v[58:59], v[226:227], v[132:133]
	s_waitcnt vmcnt(0)
	v_lshlrev_b32_e32 v224, 16, v52
	v_and_b32_e32 v225, 0xffff0000, v52
	v_lshlrev_b32_e32 v226, 16, v53
	v_and_b32_e32 v227, 0xffff0000, v53
	s_waitcnt lgkmcnt(1)
	v_pk_fma_f32 v[126:127], v[60:61], v[224:225], v[126:127]
	v_pk_fma_f32 v[128:129], v[62:63], v[226:227], v[128:129]
	v_lshlrev_b32_e32 v224, 16, v54
	v_and_b32_e32 v225, 0xffff0000, v54
	v_lshlrev_b32_e32 v226, 16, v55
	v_and_b32_e32 v227, 0xffff0000, v55
	s_waitcnt lgkmcnt(0)
	v_pk_fma_f32 v[130:131], v[220:221], v[224:225], v[130:131]
	v_pk_fma_f32 v[132:133], v[222:223], v[226:227], v[132:133]
	v_pk_mul_f32 v[224:225], v[126:127], s[18:19] op_sel_hi:[1,0]
	v_pk_mul_f32 v[226:227], v[128:129], s[18:19] op_sel_hi:[1,0]
	v_pk_mul_f32 v[2:3], v[130:131], s[18:19] op_sel_hi:[1,0]
	v_pk_mul_f32 v[134:135], v[132:133], s[18:19] op_sel_hi:[1,0]
	v_exp_f32_e32 v224, v224
	v_exp_f32_e32 v225, v225
	v_exp_f32_e32 v226, v226
	v_exp_f32_e32 v227, v227
	v_exp_f32_e32 v2, v2
	v_exp_f32_e32 v3, v3
	v_exp_f32_e32 v134, v134
	v_exp_f32_e32 v135, v135
	v_pk_add_f32 v[224:225], v[224:225], 1.0 op_sel_hi:[1,0]
	v_pk_add_f32 v[226:227], v[226:227], 1.0 op_sel_hi:[1,0]
	v_pk_add_f32 v[2:3], v[2:3], 1.0 op_sel_hi:[1,0]
	v_pk_add_f32 v[134:135], v[134:135], 1.0 op_sel_hi:[1,0]
	v_rcp_f32_e32 v224, v224
	v_rcp_f32_e32 v225, v225
	v_rcp_f32_e32 v226, v226
	v_rcp_f32_e32 v227, v227
	v_rcp_f32_e32 v2, v2
	v_rcp_f32_e32 v3, v3
	v_rcp_f32_e32 v134, v134
	v_rcp_f32_e32 v135, v135
	v_pk_mul_f32 v[68:69], v[126:127], v[224:225]
	v_pk_mul_f32 v[70:71], v[128:129], v[226:227]
	v_pk_mul_f32 v[122:123], v[130:131], v[2:3]
	v_pk_mul_f32 v[124:125], v[132:133], v[134:135]
	v_cvt_pk_bf16_f32 v224, v8, v9
	v_cvt_pk_bf16_f32 v225, v10, v11
	v_cvt_pk_bf16_f32 v226, v12, v13
	v_cvt_pk_bf16_f32 v227, v14, v15
	ds_write_b128 v117, v[224:227] offset:0
	v_cvt_pk_bf16_f32 v224, v16, v17
	v_cvt_pk_bf16_f32 v225, v18, v19
	v_cvt_pk_bf16_f32 v226, v20, v21
	v_cvt_pk_bf16_f32 v227, v22, v23
	ds_write_b128 v117, v[224:227] offset:16
	v_cvt_pk_bf16_f32 v224, v24, v25
	v_cvt_pk_bf16_f32 v225, v26, v27
	v_cvt_pk_bf16_f32 v226, v64, v65
	v_cvt_pk_bf16_f32 v227, v66, v67
	ds_write_b128 v117, v[224:227] offset:32
	v_cvt_pk_bf16_f32 v224, v68, v69
	v_cvt_pk_bf16_f32 v225, v70, v71
	v_cvt_pk_bf16_f32 v226, v122, v123
	v_cvt_pk_bf16_f32 v227, v124, v125
	ds_write_b128 v117, v[224:227] offset:48
	v_add_u32_e32 v111, v151, v149
	v_add_u32_e32 v0, v151, v143
	v_readlane_b32 s12, v252, 32
	v_readlane_b32 s13, v252, 33
	s_waitcnt lgkmcnt(0)
	s_barrier
	ds_read_b128 v[64:67], v144
	ds_read_b128 v[68:71], v144 offset:16384
	ds_read_b128 v[56:59], v146
	ds_read_b128 v[60:63], v146 offset:16384
	ds_read_b128 v[48:51], v148
	ds_read_b128 v[52:55], v148 offset:16384
	ds_read_b128 v[40:43], v150
	ds_read_b128 v[44:47], v150 offset:16384
	ds_read_b128 v[8:11], v0
	v_add_u32_e32 v2, v151, v145
	ds_read_b128 v[16:19], v2
	s_waitcnt lgkmcnt(1)
	v_mfma_f32_16x16x32_bf16 v[12:15], v[64:67], v[8:11], 0
	v_add_u32_e32 v3, v151, v147
	v_mov_b32_e32 v28, 0
	v_mov_b32_e32 v29, 0
	v_mfma_f32_16x16x32_bf16 v[8:11], v[68:71], v[8:11], 0
	v_mov_b32_e32 v30, 0
	v_mov_b32_e32 v31, 0
	v_mov_b32_e32 v24, 0
	s_waitcnt lgkmcnt(0)
	v_mfma_f32_16x16x32_bf16 v[12:15], v[56:59], v[16:19], v[12:15]
	v_mov_b32_e32 v25, 0
	v_mov_b32_e32 v26, 0
	v_mov_b32_e32 v27, 0
	v_mfma_f32_16x16x32_bf16 v[8:11], v[60:63], v[16:19], v[8:11]
	ds_read_b128 v[16:19], v3
	s_waitcnt lgkmcnt(0)
	v_mfma_f32_16x16x32_bf16 v[12:15], v[48:51], v[16:19], v[12:15]
	v_mfma_f32_16x16x32_bf16 v[8:11], v[52:55], v[16:19], v[8:11]
	ds_read_b128 v[16:19], v111
	s_waitcnt lgkmcnt(0)
	v_mfma_f32_16x16x32_bf16 v[36:39], v[40:43], v[16:19], v[12:15]
	v_mfma_f32_16x16x32_bf16 v[32:35], v[44:47], v[16:19], v[8:11]
	s_nop 3
	v_mov_b32_e32 v8, 0
	s_and_saveexec_b64 s[0:1], s[12:13]
	s_cbranch_execz .LBB0_273
	ds_read_b128 v[10:13], v0 offset:4096
	ds_read_b128 v[18:21], v2 offset:4096
	s_waitcnt lgkmcnt(1)
	v_mfma_f32_16x16x32_bf16 v[14:17], v[64:67], v[10:13], 0
	v_mfma_f32_16x16x32_bf16 v[10:13], v[68:71], v[10:13], 0
	s_waitcnt lgkmcnt(0)
	v_mfma_f32_16x16x32_bf16 v[14:17], v[56:59], v[18:21], v[14:17]
	v_mfma_f32_16x16x32_bf16 v[10:13], v[60:63], v[18:21], v[10:13]
	ds_read_b128 v[18:21], v3 offset:4096
	s_waitcnt lgkmcnt(0)
	v_mfma_f32_16x16x32_bf16 v[14:17], v[48:51], v[18:21], v[14:17]
	v_mfma_f32_16x16x32_bf16 v[10:13], v[52:55], v[18:21], v[10:13]
	ds_read_b128 v[18:21], v111 offset:4096
	s_waitcnt lgkmcnt(0)
	v_mfma_f32_16x16x32_bf16 v[28:31], v[40:43], v[18:21], v[14:17]
	v_mfma_f32_16x16x32_bf16 v[24:27], v[44:47], v[18:21], v[10:13]

.LBB0_446:
	s_cbranch_execnz .LBB0_190
	s_branch .LBB0_317
.LBB0_467:
	s_waitcnt vmcnt(0)
	s_waitcnt vmcnt(63) expcnt(7) lgkmcnt(15)
	s_barrier
	s_and_saveexec_b64 s[0:1], s[96:97]
	v_readlane_b32 s40, v251, 8
	v_readlane_b32 s41, v251, 9
	v_readlane_b32 s42, v251, 10
	v_readlane_b32 s43, v251, 11
	v_readlane_b32 s44, v251, 12
	v_readlane_b32 s45, v251, 13
	v_readlane_b32 s46, v251, 14
	v_readlane_b32 s47, v251, 15
	v_readlane_b32 s48, v251, 16
	v_readlane_b32 s49, v251, 17
	v_readlane_b32 s50, v251, 18
	v_readlane_b32 s51, v251, 19
	v_readlane_b32 s54, v251, 22
	v_readlane_b32 s55, v251, 23
	s_mov_b32 s90, s59
	s_mov_b32 s84, s62
	v_readlane_b32 s62, v252, 29
	s_mov_b64 s[86:87], s[66:67]
	v_readlane_b32 s52, v251, 20
	v_readlane_b32 s53, v251, 21
	s_cbranch_execz .LBB0_519
	v_mov_b32_e32 v0, 0x10800
	s_waitcnt vmcnt(0) expcnt(0) lgkmcnt(0)
	ds_read_b32 v2, v0
	v_mov_b32_e32 v0, 0x10804
	ds_read_b32 v0, v0
	s_waitcnt lgkmcnt(1)
	v_cmp_ne_u32_e32 vcc, 0, v2
	s_cbranch_vccnz .LBB0_483
	v_readlane_b32 s8, v252, 24
	v_readlane_b32 s9, v252, 25
	s_load_dwordx2 s[4:5], s[8:9], 0x4
	s_add_u32 s8, s44, 0x1000
	s_addc_u32 s9, s45, 0
	s_add_u32 s10, s44, 0x1100
	s_addc_u32 s11, s45, 0
	s_add_u32 s14, s44, 0x1200
	s_addc_u32 s15, s45, 0
	s_waitcnt lgkmcnt(0)
	s_mul_i32 s3, s4, s33
	s_add_u32 s16, s44, 0x1300
	s_mul_i32 s3, s3, s5
	s_addc_u32 s17, s45, 0
	s_mov_b32 s4, 1
	v_mov_b32_e32 v16, 0
	s_branch .LBB0_471
